# plus nontemporal stores of the gated FFN activation (ACT)
# baseline (speedup 1.0000x reference)
; #define LAS __attribute__((address_space(3)))
; __device__ __forceinline__ unsigned cvt_pk_bf16(float lo, float hi) { unsigned r; asm volatile("v_cvt_pk_bf16_f32 %0, %1, %2" : "=v"(r) : "v"(lo), "v"(hi)); return r; }
; __device__ __forceinline__ float sigmoidf_(float x) { return __builtin_amdgcn_rcpf(1.0f + __builtin_amdgcn_exp2f(-x * LOG2E)); }
;     __device__ __forceinline__ void operator()(const f32x4 (&acc)[2][2][4][2], const Unit& u, int wr, int wc, int fr, int fq) const {
;     ...
;             for (int ai = 0; ai < 2; ++ai) { const int blk = 2 * ai + wr;
;                 const f32x4 hpg = blk > 0 ? *(const LAS f32x4*)(xl + ((blk - 1) * 2 + 1) * 256 + colw + 4 * n) : z4;
;                 const f32x4 hpv = blk > 0 ? *(const LAS f32x4*)(xl + ((blk - 1) * 2 + 1) * 256 + 128 + colw + 4 * n) : z4;
;                 const f32x4 hng = blk < 3 ? *(const LAS f32x4*)(xl + ((blk + 1) * 2 + 0) * 256 + colw + 4 * n) : z4;
;                 const f32x4 hnv = blk < 3 ? *(const LAS f32x4*)(xl + ((blk + 1) * 2 + 0) * 256 + 128 + colw + 4 * n) : z4;
; #pragma unroll
;                 for (int m = 0; m < 4; ++m) {
;                     const f32x4 cg_ = acc[ai][0][m][n], cv_ = acc[ai][1][m][n];
;                     const f32x4 ug0 = m > 0 ? ror1v(acc[ai][0][m - 1][n]) : hpg, uv0 = m > 0 ? ror1v(acc[ai][1][m - 1][n]) : hpv;
;                     const f32x4 dg0 = m < 3 ? rol1v(acc[ai][0][m + 1][n]) : hng, dv0 = m < 3 ? rol1v(acc[ai][1][m + 1][n]) : hnv;
;                     const f32x4 ug1 = ror1v(cg_), uv1 = ror1v(cv_), dg1 = rol1v(cg_), dv1 = rol1v(cv_);
;                     f32x4 ug, uv, dg, dv;
; #pragma unroll
;                     for (int e = 0; e < 4; ++e) { ug[e] = fr == 0 ? ug0[e] : ug1[e]; uv[e] = fr == 0 ? uv0[e] : uv1[e]; dg[e] = fr == 15 ? dg0[e] : dg1[e]; dv[e] = fr == 15 ? dv0[e] : dv1[e]; }
;                     const f32x4 gc = w0g * ug + w1g * cg_ + w2g * dg + bg, vc = w0v * uv + w1v * cv_ + w2v * dv + bv;
;                     f32x4 r;
; #pragma unroll
;                     for (int e = 0; e < 4; ++e) r[e] = gc[e] * sigmoidf_(gc[e]) * vc[e];
;                     u32x2 w; w.x = cvt_pk_bf16(r[0], r[1]); w.y = cvt_pk_bf16(r[2], r[3]);
;                     *(u32x2*)(ACT + (size_t)(u.pm * BM + ai * HALF + wr * 64 + m * 16 + fr) * FF + ch) = w;
;                     asm volatile("" ::: "memory");
.LBB0_972:
	v_mov_b32_dpp v231, v130 row_ror:15 row_mask:0xf bank_mask:0xf
	v_mov_b32_dpp v235, v142 row_ror:1 row_mask:0xf bank_mask:0xf
	v_mov_b32_dpp v236, v143 row_ror:1 row_mask:0xf bank_mask:0xf
	v_mov_b32_dpp v239, v138 row_ror:1 row_mask:0xf bank_mask:0xf
	v_mov_b32_dpp v240, v139 row_ror:1 row_mask:0xf bank_mask:0xf
	v_mov_b32_dpp v190, v138 row_ror:15 row_mask:0xf bank_mask:0xf
	s_waitcnt lgkmcnt(0)
	v_cndmask_b32_e64 v193, v235, v174, s[0:1]
	v_cndmask_b32_e64 v192, v239, v170, s[0:1]
	v_cndmask_b32_e64 v196, v190, v231, s[36:37]
	s_waitcnt vmcnt(3)
	v_mov_b32_e32 v190, v166
	v_mov_b32_e32 v191, v106
	v_cndmask_b32_e64 v175, v236, v175, s[0:1]
	v_cndmask_b32_e64 v174, v240, v171, s[0:1]
	v_mov_b32_e32 v106, v167
	v_mov_b32_dpp v225, v134 row_ror:15 row_mask:0xf bank_mask:0xf
	v_mov_b32_dpp v228, v135 row_ror:15 row_mask:0xf bank_mask:0xf
	v_mov_b32_dpp v232, v131 row_ror:15 row_mask:0xf bank_mask:0xf
	v_mov_b32_dpp v0, v142 row_ror:15 row_mask:0xf bank_mask:0xf
	v_mov_b32_dpp v243, v143 row_ror:15 row_mask:0xf bank_mask:0xf
	v_mov_b32_dpp v246, v139 row_ror:15 row_mask:0xf bank_mask:0xf
	v_pk_mul_f32 v[194:195], v[190:191], v[192:193]
	v_mov_b32_e32 v226, v138
	v_mov_b32_e32 v227, v142
	s_waitcnt vmcnt(2)
	v_mov_b32_e32 v192, v162
	v_mov_b32_e32 v193, v110
	v_pk_mul_f32 v[166:167], v[106:107], v[174:175]
	v_mov_b32_e32 v142, v139
	v_mov_b32_e32 v110, v163
	v_cndmask_b32_e64 v197, v0, v225, s[36:37]
	v_pk_fma_f32 v[226:227], v[226:227], v[192:193], v[194:195]
	s_waitcnt vmcnt(1)
	v_mov_b32_e32 v194, v158
	v_mov_b32_e32 v195, v114
	v_cndmask_b32_e64 v171, v243, v228, s[36:37]
	v_cndmask_b32_e64 v170, v246, v232, s[36:37]
	v_pk_fma_f32 v[138:139], v[142:143], v[110:111], v[166:167]
	v_mov_b32_e32 v114, v159
	v_pk_fma_f32 v[226:227], v[194:195], v[196:197], v[226:227]
	v_mov_b32_e32 v197, v118
	v_pk_fma_f32 v[138:139], v[114:115], v[170:171], v[138:139]
	s_waitcnt vmcnt(0)
	v_mov_b32_e32 v118, v155
	v_pk_add_f32 v[138:139], v[118:119], v[138:139]
	v_mul_f32_e32 v142, 0xbfb8aa3b, v139
	v_exp_f32_e32 v142, v142
	v_mov_b32_dpp v237, v144 row_ror:1 row_mask:0xf bank_mask:0xf
	v_add_f32_e32 v142, 1.0, v142
	v_rcp_f32_e32 v142, v142
	v_mov_b32_dpp v241, v140 row_ror:1 row_mask:0xf bank_mask:0xf
	v_mul_f32_e32 v139, v139, v142
	v_mul_f32_e32 v170, v138, v139
	v_cndmask_b32_e64 v139, v237, v176, s[0:1]
	v_cndmask_b32_e64 v138, v241, v172, s[0:1]
	v_mov_b32_e32 v142, v168
	v_mov_b32_e32 v143, v108
	v_mov_b32_dpp v229, v136 row_ror:15 row_mask:0xf bank_mask:0xf
	v_mov_b32_dpp v233, v132 row_ror:15 row_mask:0xf bank_mask:0xf
	v_mov_b32_dpp v244, v144 row_ror:15 row_mask:0xf bank_mask:0xf
	v_mov_b32_dpp v247, v140 row_ror:15 row_mask:0xf bank_mask:0xf
	v_mov_b32_e32 v196, v154
	v_pk_mul_f32 v[138:139], v[142:143], v[138:139]
	v_mov_b32_e32 v158, v140
	v_mov_b32_e32 v159, v144
	v_mov_b32_e32 v154, v164
	v_mov_b32_e32 v155, v112
	v_cndmask_b32_e64 v163, v244, v229, s[36:37]
	v_cndmask_b32_e64 v162, v247, v233, s[36:37]
	v_pk_fma_f32 v[138:139], v[158:159], v[154:155], v[138:139]
	v_mov_b32_e32 v158, v160
	v_mov_b32_e32 v159, v116
	v_pk_fma_f32 v[138:139], v[158:159], v[162:163], v[138:139]
	v_mov_b32_e32 v162, v156
	v_mov_b32_e32 v163, v120
	v_pk_add_f32 v[138:139], v[162:163], v[138:139]
	v_mul_f32_e32 v108, 0xbfb8aa3b, v139
	v_exp_f32_e32 v108, v108
	v_mov_b32_dpp v238, v145 row_ror:1 row_mask:0xf bank_mask:0xf
	v_add_f32_e32 v108, 1.0, v108
	v_rcp_f32_e32 v108, v108
	v_mov_b32_dpp v242, v141 row_ror:1 row_mask:0xf bank_mask:0xf
	v_mul_f32_e32 v108, v139, v108
	v_mul_f32_e32 v140, v138, v108
	v_cndmask_b32_e64 v139, v238, v177, s[0:1]
	v_cndmask_b32_e64 v138, v242, v173, s[0:1]
	v_mov_b32_e32 v108, v169
	v_mov_b32_dpp v230, v137 row_ror:15 row_mask:0xf bank_mask:0xf
	v_mov_b32_dpp v234, v133 row_ror:15 row_mask:0xf bank_mask:0xf
	v_mov_b32_dpp v245, v145 row_ror:15 row_mask:0xf bank_mask:0xf
	v_mov_b32_dpp v248, v141 row_ror:15 row_mask:0xf bank_mask:0xf
	v_pk_mul_f32 v[138:139], v[108:109], v[138:139]
	v_mov_b32_e32 v144, v141
	v_mov_b32_e32 v112, v165
	v_cndmask_b32_e64 v167, v245, v230, s[36:37]
	v_cndmask_b32_e64 v166, v248, v234, s[36:37]
	v_pk_fma_f32 v[138:139], v[144:145], v[112:113], v[138:139]
	v_mov_b32_e32 v116, v161
	v_pk_add_f32 v[226:227], v[196:197], v[226:227]
	v_pk_fma_f32 v[138:139], v[116:117], v[166:167], v[138:139]
	v_mov_b32_e32 v120, v157
	v_mul_f32_e32 v0, 0xbfb8aa3b, v227
	v_pk_add_f32 v[138:139], v[120:121], v[138:139]
	v_exp_f32_e32 v0, v0
	v_mul_f32_e32 v141, 0xbfb8aa3b, v139
	v_exp_f32_e32 v141, v141
	s_lshl_b32 s20, s21, 8
	v_add_f32_e32 v0, 1.0, v0
	v_rcp_f32_e32 v0, v0
	v_add_f32_e32 v141, 1.0, v141
	v_rcp_f32_e32 v141, v141
	v_mov_b64_e32 v[144:145], s[84:85]
	v_mul_f32_e32 v0, v227, v0
	v_mul_f32_e32 v0, v226, v0
	v_mul_f32_e32 v139, v139, v141
	v_mul_f32_e32 v138, v138, v139
	v_cvt_pk_bf16_f32 v156, v0, v170
	v_add_u32_e32 v0, s20, v213
	v_cvt_pk_bf16_f32 v157, v140, v138
	v_mad_i64_i32 v[138:139], s[24:25], v0, s90, v[144:145]
	v_lshlrev_b64 v[140:141], 1, v[186:187]
	v_lshl_add_u64 v[138:139], v[138:139], 0, v[140:141]
	v_mov_b32_dpp v174, v134 row_ror:1 row_mask:0xf bank_mask:0xf
	v_mov_b32_dpp v187, v130 row_ror:1 row_mask:0xf bank_mask:0xf
	global_store_dwordx2 v[138:139], v[156:157], off nt
	v_cndmask_b32_e64 v157, v174, v235, s[0:1]
	v_cndmask_b32_e64 v156, v187, v239, s[0:1]
	v_mov_b32_dpp v166, v126 row_ror:15 row_mask:0xf bank_mask:0xf
	v_mov_b32_dpp v170, v122 row_ror:15 row_mask:0xf bank_mask:0xf
	v_pk_mul_f32 v[156:157], v[190:191], v[156:157]
	v_mov_b32_e32 v164, v130
	v_mov_b32_e32 v165, v134
	v_cndmask_b32_e64 v161, v225, v166, s[36:37]
	v_cndmask_b32_e64 v160, v231, v170, s[36:37]
; __device__ __forceinline__ unsigned cvt_pk_bf16(float lo, float hi) { unsigned r; asm volatile("v_cvt_pk_bf16_f32 %0, %1, %2" : "=v"(r) : "v"(lo), "v"(hi)); return r; }
; __device__ __forceinline__ float sigmoidf_(float x) { return __builtin_amdgcn_rcpf(1.0f + __builtin_amdgcn_exp2f(-x * LOG2E)); }
; __device__ __forceinline__ f32x4 ror1v(const f32x4 v) { return (f32x4){dpp_ror1(v[0]), dpp_ror1(v[1]), dpp_ror1(v[2]), dpp_ror1(v[3])}; }
; __device__ __forceinline__ f32x4 rol1v(const f32x4 v) { return (f32x4){dpp_rol1(v[0]), dpp_rol1(v[1]), dpp_rol1(v[2]), dpp_rol1(v[3])}; }
;     __device__ __forceinline__ void operator()(const f32x4 (&acc)[2][2][4][2], const Unit& u, int wr, int wc, int fr, int fq) const {
;     ...
;                 for (int m = 0; m < 4; ++m) {
;                     const f32x4 cg_ = acc[ai][0][m][n], cv_ = acc[ai][1][m][n];
;                     const f32x4 ug0 = m > 0 ? ror1v(acc[ai][0][m - 1][n]) : hpg, uv0 = m > 0 ? ror1v(acc[ai][1][m - 1][n]) : hpv;
;                     const f32x4 dg0 = m < 3 ? rol1v(acc[ai][0][m + 1][n]) : hng, dv0 = m < 3 ? rol1v(acc[ai][1][m + 1][n]) : hnv;
;                     const f32x4 ug1 = ror1v(cg_), uv1 = ror1v(cv_), dg1 = rol1v(cg_), dv1 = rol1v(cv_);
;                     f32x4 ug, uv, dg, dv;
; #pragma unroll
;                     for (int e = 0; e < 4; ++e) { ug[e] = fr == 0 ? ug0[e] : ug1[e]; uv[e] = fr == 0 ? uv0[e] : uv1[e]; dg[e] = fr == 15 ? dg0[e] : dg1[e]; dv[e] = fr == 15 ? dv0[e] : dv1[e]; }
;                     const f32x4 gc = w0g * ug + w1g * cg_ + w2g * dg + bg, vc = w0v * uv + w1v * cv_ + w2v * dv + bv;
;                     f32x4 r;
; #pragma unroll
;                     for (int e = 0; e < 4; ++e) r[e] = gc[e] * sigmoidf_(gc[e]) * vc[e];
;                     u32x2 w; w.x = cvt_pk_bf16(r[0], r[1]); w.y = cvt_pk_bf16(r[2], r[3]);
;                     *(u32x2*)(ACT + (size_t)(u.pm * BM + ai * HALF + wr * 64 + m * 16 + fr) * FF + ch) = w;
;                     asm volatile("" ::: "memory");
	v_pk_fma_f32 v[156:157], v[164:165], v[192:193], v[156:157]
	v_pk_fma_f32 v[156:157], v[194:195], v[160:161], v[156:157]
	v_pk_add_f32 v[156:157], v[196:197], v[156:157]
	v_mov_b32_dpp v175, v135 row_ror:1 row_mask:0xf bank_mask:0xf
	v_mul_f32_e32 v130, 0xbfb8aa3b, v157
	v_exp_f32_e32 v130, v130
	v_mov_b32_dpp v226, v131 row_ror:1 row_mask:0xf bank_mask:0xf
	v_add_f32_e32 v130, 1.0, v130
	v_rcp_f32_e32 v130, v130
	v_mov_b32_dpp v167, v127 row_ror:15 row_mask:0xf bank_mask:0xf
	v_mov_b32_dpp v171, v123 row_ror:15 row_mask:0xf bank_mask:0xf
	v_mov_b32_e32 v134, v131
	v_mul_f32_e32 v130, v157, v130
	v_mul_f32_e32 v164, v156, v130
	v_cndmask_b32_e64 v157, v175, v236, s[0:1]
	v_cndmask_b32_e64 v156, v226, v240, s[0:1]
	v_pk_mul_f32 v[156:157], v[106:107], v[156:157]
	v_cndmask_b32_e64 v161, v228, v167, s[36:37]
	v_cndmask_b32_e64 v160, v232, v171, s[36:37]
	v_pk_fma_f32 v[130:131], v[134:135], v[110:111], v[156:157]
	v_pk_fma_f32 v[130:131], v[114:115], v[160:161], v[130:131]
	v_pk_add_f32 v[130:131], v[118:119], v[130:131]
	v_mov_b32_dpp v176, v136 row_ror:1 row_mask:0xf bank_mask:0xf
	v_mul_f32_e32 v134, 0xbfb8aa3b, v131
	v_exp_f32_e32 v134, v134
	v_mov_b32_dpp v227, v132 row_ror:1 row_mask:0xf bank_mask:0xf
	v_add_f32_e32 v134, 1.0, v134
	v_rcp_f32_e32 v134, v134
	v_mov_b32_dpp v168, v128 row_ror:15 row_mask:0xf bank_mask:0xf
	v_mov_b32_dpp v172, v124 row_ror:15 row_mask:0xf bank_mask:0xf
	v_mov_b32_e32 v156, v132
	v_mul_f32_e32 v131, v131, v134
	v_mul_f32_e32 v160, v130, v131
	v_cndmask_b32_e64 v131, v176, v237, s[0:1]
	v_cndmask_b32_e64 v130, v227, v241, s[0:1]
	v_pk_mul_f32 v[130:131], v[142:143], v[130:131]
	v_mov_b32_e32 v157, v136
	v_cndmask_b32_e64 v135, v229, v168, s[36:37]
	v_cndmask_b32_e64 v134, v233, v172, s[36:37]
	v_pk_fma_f32 v[130:131], v[156:157], v[154:155], v[130:131]
	v_pk_fma_f32 v[130:131], v[158:159], v[134:135], v[130:131]
	v_pk_add_f32 v[130:131], v[162:163], v[130:131]
	v_mov_b32_dpp v177, v137 row_ror:1 row_mask:0xf bank_mask:0xf
	v_mul_f32_e32 v132, 0xbfb8aa3b, v131
	v_exp_f32_e32 v132, v132
	v_mov_b32_dpp v243, v133 row_ror:1 row_mask:0xf bank_mask:0xf
	v_add_f32_e32 v132, 1.0, v132
	v_rcp_f32_e32 v132, v132
	v_mov_b32_dpp v169, v129 row_ror:15 row_mask:0xf bank_mask:0xf
	v_mov_b32_dpp v173, v125 row_ror:15 row_mask:0xf bank_mask:0xf
	v_mov_b32_e32 v136, v133
	v_mul_f32_e32 v131, v131, v132
	v_mul_f32_e32 v156, v130, v131
	v_cndmask_b32_e64 v131, v177, v238, s[0:1]
	v_cndmask_b32_e64 v130, v243, v242, s[0:1]
	v_pk_mul_f32 v[130:131], v[108:109], v[130:131]
	v_cndmask_b32_e64 v135, v230, v169, s[36:37]
	v_cndmask_b32_e64 v134, v234, v173, s[36:37]
	v_pk_fma_f32 v[130:131], v[136:137], v[112:113], v[130:131]
	v_pk_fma_f32 v[130:131], v[116:117], v[134:135], v[130:131]
	v_pk_add_f32 v[130:131], v[120:121], v[130:131]
	v_mov_b32_dpp v229, v126 row_ror:1 row_mask:0xf bank_mask:0xf
	v_mul_f32_e32 v132, 0xbfb8aa3b, v131
	v_exp_f32_e32 v132, v132
	v_mov_b32_dpp v233, v122 row_ror:1 row_mask:0xf bank_mask:0xf
	v_mov_b32_e32 v136, v122
	v_mov_b32_e32 v137, v126
	v_add_f32_e32 v132, 1.0, v132
	v_rcp_f32_e32 v132, v132
	s_nop 0
	v_mul_f32_e32 v131, v131, v132
	v_mul_f32_e32 v130, v130, v131
	v_cvt_pk_bf16_f32 v132, v164, v160
	v_cvt_pk_bf16_f32 v133, v156, v130
	v_add_u32_e32 v130, s20, v215
	v_mad_i64_i32 v[130:131], s[24:25], v130, s90, v[144:145]
	v_lshl_add_u64 v[130:131], v[130:131], 0, v[140:141]
	global_store_dwordx2 v[130:131], v[132:133], off nt
	v_cndmask_b32_e64 v133, v229, v174, s[0:1]
	v_cndmask_b32_e64 v132, v233, v187, s[0:1]
	v_mov_b32_dpp v156, v102 row_ror:15 row_mask:0xf bank_mask:0xf
	v_mov_b32_dpp v164, v98 row_ror:15 row_mask:0xf bank_mask:0xf
	v_pk_mul_f32 v[132:133], v[190:191], v[132:133]
	v_cndmask_b32_e64 v135, v166, v156, s[36:37]
	v_cndmask_b32_e64 v134, v170, v164, s[36:37]
	v_pk_fma_f32 v[132:133], v[136:137], v[192:193], v[132:133]
	v_mov_b32_dpp v230, v127 row_ror:1 row_mask:0xf bank_mask:0xf
	v_pk_fma_f32 v[132:133], v[194:195], v[134:135], v[132:133]
	v_mov_b32_dpp v234, v123 row_ror:1 row_mask:0xf bank_mask:0xf
	v_pk_add_f32 v[132:133], v[196:197], v[132:133]
	v_mul_f32_e32 v122, 0xbfb8aa3b, v133
	v_exp_f32_e32 v122, v122
	v_mov_b32_dpp v157, v103 row_ror:15 row_mask:0xf bank_mask:0xf
	v_mov_b32_dpp v165, v99 row_ror:15 row_mask:0xf bank_mask:0xf
	v_mov_b32_e32 v126, v123
	v_add_f32_e32 v122, 1.0, v122
	v_rcp_f32_e32 v122, v122
	v_cndmask_b32_e64 v135, v167, v157, s[36:37]
	v_cndmask_b32_e64 v134, v171, v165, s[36:37]
	v_mul_f32_e32 v122, v133, v122
	v_mul_f32_e32 v136, v132, v122
	v_cndmask_b32_e64 v133, v230, v175, s[0:1]
	v_cndmask_b32_e64 v132, v234, v226, s[0:1]
	v_pk_mul_f32 v[132:133], v[106:107], v[132:133]
	v_pk_fma_f32 v[122:123], v[126:127], v[110:111], v[132:133]
	v_mov_b32_dpp v231, v128 row_ror:1 row_mask:0xf bank_mask:0xf
	v_pk_fma_f32 v[122:123], v[114:115], v[134:135], v[122:123]
	v_mov_b32_dpp v235, v124 row_ror:1 row_mask:0xf bank_mask:0xf
	v_pk_add_f32 v[122:123], v[118:119], v[122:123]
	v_mul_f32_e32 v126, 0xbfb8aa3b, v123
	v_exp_f32_e32 v126, v126
	v_mov_b32_dpp v160, v104 row_ror:15 row_mask:0xf bank_mask:0xf
	v_mov_b32_e32 v132, v124
	v_add_f32_e32 v126, 1.0, v126
	v_rcp_f32_e32 v126, v126
	v_mov_b32_dpp v225, v100 row_ror:15 row_mask:0xf bank_mask:0xf
	v_mov_b32_e32 v133, v128
	v_cndmask_b32_e64 v127, v168, v160, s[36:37]
; #define LAS __attribute__((address_space(3)))
; __device__ __forceinline__ unsigned cvt_pk_bf16(float lo, float hi) { unsigned r; asm volatile("v_cvt_pk_bf16_f32 %0, %1, %2" : "=v"(r) : "v"(lo), "v"(hi)); return r; }
; __device__ __forceinline__ float sigmoidf_(float x) { return __builtin_amdgcn_rcpf(1.0f + __builtin_amdgcn_exp2f(-x * LOG2E)); }
; __device__ __forceinline__ f32x4 ror1v(const f32x4 v) { return (f32x4){dpp_ror1(v[0]), dpp_ror1(v[1]), dpp_ror1(v[2]), dpp_ror1(v[3])}; }
;     __device__ __forceinline__ void operator()(const f32x4 (&acc)[2][2][4][2], const Unit& u, int wr, int wc, int fr, int fq) const {
;     ...
;                 const f32x4 hpg = blk > 0 ? *(const LAS f32x4*)(xl + ((blk - 1) * 2 + 1) * 256 + colw + 4 * n) : z4;
;                 const f32x4 hpv = blk > 0 ? *(const LAS f32x4*)(xl + ((blk - 1) * 2 + 1) * 256 + 128 + colw + 4 * n) : z4;
;                 const f32x4 hng = blk < 3 ? *(const LAS f32x4*)(xl + ((blk + 1) * 2 + 0) * 256 + colw + 4 * n) : z4;
;                 const f32x4 hnv = blk < 3 ? *(const LAS f32x4*)(xl + ((blk + 1) * 2 + 0) * 256 + 128 + colw + 4 * n) : z4;
;     ...
;                 for (int m = 0; m < 4; ++m) {
;                     const f32x4 cg_ = acc[ai][0][m][n], cv_ = acc[ai][1][m][n];
;                     const f32x4 ug0 = m > 0 ? ror1v(acc[ai][0][m - 1][n]) : hpg, uv0 = m > 0 ? ror1v(acc[ai][1][m - 1][n]) : hpv;
;                     const f32x4 dg0 = m < 3 ? rol1v(acc[ai][0][m + 1][n]) : hng, dv0 = m < 3 ? rol1v(acc[ai][1][m + 1][n]) : hnv;
;                     const f32x4 ug1 = ror1v(cg_), uv1 = ror1v(cv_), dg1 = rol1v(cg_), dv1 = rol1v(cv_);
;                     f32x4 ug, uv, dg, dv;
; #pragma unroll
;                     for (int e = 0; e < 4; ++e) { ug[e] = fr == 0 ? ug0[e] : ug1[e]; uv[e] = fr == 0 ? uv0[e] : uv1[e]; dg[e] = fr == 15 ? dg0[e] : dg1[e]; dv[e] = fr == 15 ? dv0[e] : dv1[e]; }
;                     const f32x4 gc = w0g * ug + w1g * cg_ + w2g * dg + bg, vc = w0v * uv + w1v * cv_ + w2v * dv + bv;
;                     f32x4 r;
; #pragma unroll
;                     for (int e = 0; e < 4; ++e) r[e] = gc[e] * sigmoidf_(gc[e]) * vc[e];
;                     u32x2 w; w.x = cvt_pk_bf16(r[0], r[1]); w.y = cvt_pk_bf16(r[2], r[3]);
;                     *(u32x2*)(ACT + (size_t)(u.pm * BM + ai * HALF + wr * 64 + m * 16 + fr) * FF + ch) = w;
;                     asm volatile("" ::: "memory");
	v_mul_f32_e32 v123, v123, v126
	v_mul_f32_e32 v134, v122, v123
	v_cndmask_b32_e64 v123, v231, v176, s[0:1]
	v_cndmask_b32_e64 v122, v235, v227, s[0:1]
	v_pk_mul_f32 v[122:123], v[142:143], v[122:123]
	v_cndmask_b32_e64 v126, v172, v225, s[36:37]
	v_pk_fma_f32 v[122:123], v[132:133], v[154:155], v[122:123]
	v_pk_fma_f32 v[122:123], v[158:159], v[126:127], v[122:123]
	v_pk_add_f32 v[122:123], v[162:163], v[122:123]
	v_mov_b32_dpp v232, v129 row_ror:1 row_mask:0xf bank_mask:0xf
	v_mul_f32_e32 v124, 0xbfb8aa3b, v123
	v_exp_f32_e32 v124, v124
	v_mov_b32_dpp v236, v125 row_ror:1 row_mask:0xf bank_mask:0xf
	v_add_f32_e32 v124, 1.0, v124
	v_rcp_f32_e32 v124, v124
	v_mov_b32_dpp v161, v105 row_ror:15 row_mask:0xf bank_mask:0xf
	v_mov_b32_dpp v228, v101 row_ror:15 row_mask:0xf bank_mask:0xf
	v_mov_b32_e32 v128, v125
	v_mul_f32_e32 v123, v123, v124
	v_mul_f32_e32 v124, v122, v123
	v_cndmask_b32_e64 v123, v232, v177, s[0:1]
	v_cndmask_b32_e64 v122, v236, v243, s[0:1]
	v_pk_mul_f32 v[122:123], v[108:109], v[122:123]
	v_cndmask_b32_e64 v127, v169, v161, s[36:37]
	v_cndmask_b32_e64 v126, v173, v228, s[36:37]
	v_pk_fma_f32 v[122:123], v[128:129], v[112:113], v[122:123]
	v_pk_fma_f32 v[122:123], v[116:117], v[126:127], v[122:123]
	v_mov_b32_e32 v126, v98
	v_pk_add_f32 v[122:123], v[120:121], v[122:123]
	v_mov_b32_e32 v127, v102
	v_mul_f32_e32 v125, 0xbfb8aa3b, v123
	v_exp_f32_e32 v125, v125
	v_mov_b32_dpp v128, v103 row_ror:1 row_mask:0xf bank_mask:0xf
	v_add_f32_e32 v125, 1.0, v125
	v_rcp_f32_e32 v125, v125
	v_mov_b32_dpp v135, v99 row_ror:1 row_mask:0xf bank_mask:0xf
	v_mov_b32_dpp v129, v104 row_ror:1 row_mask:0xf bank_mask:0xf
	v_mul_f32_e32 v123, v123, v125
	v_mul_f32_e32 v123, v122, v123
	v_cvt_pk_bf16_f32 v122, v136, v134
	v_cvt_pk_bf16_f32 v123, v124, v123
	v_add_u32_e32 v124, s20, v216
	v_mad_i64_i32 v[124:125], s[24:25], v124, s90, v[144:145]
	v_lshl_add_u64 v[132:133], v[124:125], 0, v[140:141]
	global_store_dwordx2 v[132:133], v[122:123], off nt
	v_cndmask_b32_e64 v125, v156, v150, s[36:37]
	v_mov_b32_dpp v122, v102 row_ror:1 row_mask:0xf bank_mask:0xf
	v_mov_b32_dpp v124, v98 row_ror:1 row_mask:0xf bank_mask:0xf
	v_cndmask_b32_e64 v123, v122, v229, s[0:1]
	v_cndmask_b32_e64 v122, v124, v233, s[0:1]
	v_pk_mul_f32 v[122:123], v[190:191], v[122:123]
	v_cndmask_b32_e64 v124, v164, v146, s[36:37]
	v_pk_fma_f32 v[122:123], v[126:127], v[192:193], v[122:123]
	v_mov_b32_e32 v102, v99
	v_pk_fma_f32 v[122:123], v[194:195], v[124:125], v[122:123]
	v_cndmask_b32_e64 v125, v157, v151, s[36:37]
	v_pk_add_f32 v[122:123], v[196:197], v[122:123]
	v_cndmask_b32_e64 v124, v165, v147, s[36:37]
	v_mul_f32_e32 v98, 0xbfb8aa3b, v123
	v_exp_f32_e32 v98, v98
	v_mov_b32_dpp v137, v101 row_ror:1 row_mask:0xf bank_mask:0xf
	v_add_f32_e32 v98, 1.0, v98
	v_rcp_f32_e32 v98, v98
	v_mov_b32_dpp v136, v100 row_ror:1 row_mask:0xf bank_mask:0xf
	v_mov_b32_dpp v134, v105 row_ror:1 row_mask:0xf bank_mask:0xf
	v_mul_f32_e32 v98, v123, v98
	v_mul_f32_e32 v126, v122, v98
	v_cndmask_b32_e64 v123, v128, v230, s[0:1]
	v_cndmask_b32_e64 v122, v135, v234, s[0:1]
	v_pk_mul_f32 v[122:123], v[106:107], v[122:123]
	s_andn2_b64 vcc, exec, s[16:17]
	v_pk_fma_f32 v[98:99], v[102:103], v[110:111], v[122:123]
	v_mov_b32_e32 v122, v100
	v_pk_fma_f32 v[98:99], v[114:115], v[124:125], v[98:99]
	v_mov_b32_e32 v123, v104
	v_pk_add_f32 v[98:99], v[118:119], v[98:99]
	v_cndmask_b32_e64 v103, v160, v152, s[36:37]
	v_mul_f32_e32 v102, 0xbfb8aa3b, v99
	v_exp_f32_e32 v102, v102
	v_mov_b32_e32 v104, v101
	v_mov_b32_e32 v127, 0
	v_mov_b32_e32 v128, 0
	v_add_f32_e32 v102, 1.0, v102
	v_rcp_f32_e32 v102, v102
	s_nop 0
	v_mul_f32_e32 v99, v99, v102
	v_mul_f32_e32 v124, v98, v99
	v_cndmask_b32_e64 v99, v129, v231, s[0:1]
	v_cndmask_b32_e64 v98, v136, v235, s[0:1]
	v_pk_mul_f32 v[98:99], v[142:143], v[98:99]
	v_cndmask_b32_e64 v102, v225, v148, s[36:37]
	v_pk_fma_f32 v[98:99], v[122:123], v[154:155], v[98:99]
	v_mov_b32_e32 v122, 0
	v_pk_fma_f32 v[98:99], v[158:159], v[102:103], v[98:99]
	v_cndmask_b32_e64 v103, v161, v153, s[36:37]
	v_pk_add_f32 v[98:99], v[162:163], v[98:99]
	v_cndmask_b32_e64 v102, v228, v149, s[36:37]
	v_mul_f32_e32 v100, 0xbfb8aa3b, v99
	v_exp_f32_e32 v100, v100
	v_mov_b32_e32 v129, 0
	v_add_f32_e32 v100, 1.0, v100
	v_rcp_f32_e32 v100, v100
	s_nop 0
	v_mul_f32_e32 v99, v99, v100
	v_mul_f32_e32 v100, v98, v99
	v_cndmask_b32_e64 v99, v134, v232, s[0:1]
	v_cndmask_b32_e64 v98, v137, v236, s[0:1]
	v_pk_mul_f32 v[98:99], v[108:109], v[98:99]
	s_nop 0
	v_pk_fma_f32 v[98:99], v[104:105], v[112:113], v[98:99]
	s_nop 0
	v_pk_fma_f32 v[98:99], v[116:117], v[102:103], v[98:99]
	s_nop 0
	v_pk_add_f32 v[98:99], v[120:121], v[98:99]
	s_nop 0
	v_mul_f32_e32 v101, 0xbfb8aa3b, v99
	v_exp_f32_e32 v101, v101
	s_nop 0
	v_add_f32_e32 v101, 1.0, v101
	v_rcp_f32_e32 v101, v101
	s_nop 0
	v_mul_f32_e32 v99, v99, v101
	v_mul_f32_e32 v99, v98, v99
	v_cvt_pk_bf16_f32 v98, v126, v124
	v_cvt_pk_bf16_f32 v99, v100, v99
	v_add_u32_e32 v100, s20, v217
	v_mad_i64_i32 v[100:101], s[20:21], v100, s90, v[144:145]
	v_lshl_add_u64 v[134:135], v[100:101], 0, v[140:141]
	global_store_dwordx2 v[134:135], v[98:99], off nt
	v_cndmask_b32_e64 v98, 0, 1, s[16:17]
	v_cmp_ne_u32_e64 s[46:47], 1, v98
	v_mov_b32_e32 v126, 0
	s_cbranch_vccnz .LBB0_974
	ds_read_b128 v[126:129], v218 offset:3072

; __device__ __forceinline__ unsigned cvt_pk_bf16(float lo, float hi) { unsigned r; asm volatile("v_cvt_pk_bf16_f32 %0, %1, %2" : "=v"(r) : "v"(lo), "v"(hi)); return r; }
; __device__ __forceinline__ float sigmoidf_(float x) { return __builtin_amdgcn_rcpf(1.0f + __builtin_amdgcn_exp2f(-x * LOG2E)); }
; __device__ __forceinline__ f32x4 ror1v(const f32x4 v) { return (f32x4){dpp_ror1(v[0]), dpp_ror1(v[1]), dpp_ror1(v[2]), dpp_ror1(v[3])}; }
; __device__ __forceinline__ f32x4 rol1v(const f32x4 v) { return (f32x4){dpp_rol1(v[0]), dpp_rol1(v[1]), dpp_rol1(v[2]), dpp_rol1(v[3])}; }
;     __device__ __forceinline__ void operator()(const f32x4 (&acc)[2][2][4][2], const Unit& u, int wr, int wc, int fr, int fq) const {
;     ...
;                 for (int m = 0; m < 4; ++m) {
;                     const f32x4 cg_ = acc[ai][0][m][n], cv_ = acc[ai][1][m][n];
;                     const f32x4 ug0 = m > 0 ? ror1v(acc[ai][0][m - 1][n]) : hpg, uv0 = m > 0 ? ror1v(acc[ai][1][m - 1][n]) : hpv;
;                     const f32x4 dg0 = m < 3 ? rol1v(acc[ai][0][m + 1][n]) : hng, dv0 = m < 3 ? rol1v(acc[ai][1][m + 1][n]) : hnv;
;                     const f32x4 ug1 = ror1v(cg_), uv1 = ror1v(cv_), dg1 = rol1v(cg_), dv1 = rol1v(cv_);
;                     f32x4 ug, uv, dg, dv;
; #pragma unroll
;                     for (int e = 0; e < 4; ++e) { ug[e] = fr == 0 ? ug0[e] : ug1[e]; uv[e] = fr == 0 ? uv0[e] : uv1[e]; dg[e] = fr == 15 ? dg0[e] : dg1[e]; dv[e] = fr == 15 ? dv0[e] : dv1[e]; }
;                     const f32x4 gc = w0g * ug + w1g * cg_ + w2g * dg + bg, vc = w0v * uv + w1v * cv_ + w2v * dv + bv;
;                     f32x4 r;
; #pragma unroll
;                     for (int e = 0; e < 4; ++e) r[e] = gc[e] * sigmoidf_(gc[e]) * vc[e];
;                     u32x2 w; w.x = cvt_pk_bf16(r[0], r[1]); w.y = cvt_pk_bf16(r[2], r[3]);
;                     *(u32x2*)(ACT + (size_t)(u.pm * BM + ai * HALF + wr * 64 + m * 16 + fr) * FF + ch) = w;
;                     asm volatile("" ::: "memory");
.LBB0_980:
	v_mov_b32_dpp v160, v94 row_ror:1 row_mask:0xf bank_mask:0xf
	v_mov_b32_dpp v166, v90 row_ror:1 row_mask:0xf bank_mask:0xf
	v_mov_b32_dpp v148, v86 row_ror:15 row_mask:0xf bank_mask:0xf
	v_mov_b32_dpp v152, v82 row_ror:15 row_mask:0xf bank_mask:0xf
	v_mov_b32_dpp v144, v94 row_ror:15 row_mask:0xf bank_mask:0xf
	v_mov_b32_dpp v146, v90 row_ror:15 row_mask:0xf bank_mask:0xf
	s_waitcnt lgkmcnt(0)
	v_cndmask_b32_e64 v137, v160, v126, s[0:1]
	v_cndmask_b32_e64 v136, v166, v122, s[0:1]
	v_cndmask_b32_e64 v145, v144, v148, s[36:37]
	v_cndmask_b32_e64 v144, v146, v152, s[36:37]
	v_pk_mul_f32 v[136:137], v[190:191], v[136:137]
	v_mov_b32_e32 v146, v90
	v_mov_b32_e32 v147, v94
	v_pk_fma_f32 v[136:137], v[146:147], v[192:193], v[136:137]
	v_pk_fma_f32 v[136:137], v[194:195], v[144:145], v[136:137]
	v_pk_add_f32 v[136:137], v[196:197], v[136:137]
	v_mov_b32_dpp v161, v95 row_ror:1 row_mask:0xf bank_mask:0xf
	v_mul_f32_e32 v90, 0xbfb8aa3b, v137
	v_exp_f32_e32 v90, v90
	v_mov_b32_dpp v167, v91 row_ror:1 row_mask:0xf bank_mask:0xf
	v_add_f32_e32 v90, 1.0, v90
	v_rcp_f32_e32 v90, v90
	v_cndmask_b32_e64 v127, v161, v127, s[0:1]
	v_cndmask_b32_e64 v126, v167, v123, s[0:1]
	v_mov_b32_dpp v149, v87 row_ror:15 row_mask:0xf bank_mask:0xf
	v_mov_b32_dpp v153, v83 row_ror:15 row_mask:0xf bank_mask:0xf
	v_mov_b32_dpp v170, v95 row_ror:15 row_mask:0xf bank_mask:0xf
	v_mov_b32_dpp v173, v91 row_ror:15 row_mask:0xf bank_mask:0xf
	v_mul_f32_e32 v90, v137, v90
	v_pk_mul_f32 v[126:127], v[106:107], v[126:127]
	v_mov_b32_e32 v94, v91
	v_mul_f32_e32 v136, v136, v90
	v_cndmask_b32_e64 v123, v170, v149, s[36:37]
	v_cndmask_b32_e64 v122, v173, v153, s[36:37]
	v_pk_fma_f32 v[90:91], v[94:95], v[110:111], v[126:127]
	v_pk_fma_f32 v[90:91], v[114:115], v[122:123], v[90:91]
	v_pk_add_f32 v[90:91], v[118:119], v[90:91]
	v_mov_b32_dpp v164, v96 row_ror:1 row_mask:0xf bank_mask:0xf
	v_mul_f32_e32 v94, 0xbfb8aa3b, v91
	v_exp_f32_e32 v94, v94
	v_mov_b32_dpp v168, v92 row_ror:1 row_mask:0xf bank_mask:0xf
	v_add_f32_e32 v94, 1.0, v94
	v_rcp_f32_e32 v94, v94
	v_mov_b32_dpp v150, v88 row_ror:15 row_mask:0xf bank_mask:0xf
	v_mul_f32_e32 v91, v91, v94
	v_mul_f32_e32 v126, v90, v91
	v_cndmask_b32_e64 v91, v164, v128, s[0:1]
	v_cndmask_b32_e64 v90, v168, v124, s[0:1]
	v_mov_b32_dpp v156, v84 row_ror:15 row_mask:0xf bank_mask:0xf
	v_mov_b32_dpp v171, v96 row_ror:15 row_mask:0xf bank_mask:0xf
	v_mov_b32_dpp v174, v92 row_ror:15 row_mask:0xf bank_mask:0xf
	v_pk_mul_f32 v[90:91], v[142:143], v[90:91]
	v_mov_b32_e32 v122, v92
	v_mov_b32_e32 v123, v96
	v_cndmask_b32_e64 v95, v171, v150, s[36:37]
	v_cndmask_b32_e64 v94, v174, v156, s[36:37]
	v_pk_fma_f32 v[90:91], v[122:123], v[154:155], v[90:91]
	v_pk_fma_f32 v[90:91], v[158:159], v[94:95], v[90:91]
	v_pk_add_f32 v[90:91], v[162:163], v[90:91]
	v_mov_b32_dpp v165, v97 row_ror:1 row_mask:0xf bank_mask:0xf
	v_mul_f32_e32 v92, 0xbfb8aa3b, v91
	v_exp_f32_e32 v92, v92
	v_mov_b32_dpp v169, v93 row_ror:1 row_mask:0xf bank_mask:0xf
	v_add_f32_e32 v92, 1.0, v92
	v_rcp_f32_e32 v92, v92
	v_mov_b32_dpp v151, v89 row_ror:15 row_mask:0xf bank_mask:0xf
	v_mul_f32_e32 v91, v91, v92
	v_mul_f32_e32 v122, v90, v91
	v_cndmask_b32_e64 v91, v165, v129, s[0:1]
	v_cndmask_b32_e64 v90, v169, v125, s[0:1]
	v_mov_b32_dpp v157, v85 row_ror:15 row_mask:0xf bank_mask:0xf
	v_mov_b32_dpp v172, v97 row_ror:15 row_mask:0xf bank_mask:0xf
	v_mov_b32_dpp v175, v93 row_ror:15 row_mask:0xf bank_mask:0xf
	v_pk_mul_f32 v[90:91], v[108:109], v[90:91]
	v_mov_b32_e32 v96, v93
	v_cndmask_b32_e64 v95, v172, v151, s[36:37]
	v_cndmask_b32_e64 v94, v175, v157, s[36:37]
	v_pk_fma_f32 v[90:91], v[96:97], v[112:113], v[90:91]
	v_pk_fma_f32 v[90:91], v[116:117], v[94:95], v[90:91]
	v_add_u32_e32 v94, 0x80, v0
	v_pk_add_f32 v[90:91], v[120:121], v[90:91]
	v_mul_f32_e32 v92, 0xbfb8aa3b, v91
	v_exp_f32_e32 v92, v92
	v_mov_b32_dpp v146, v86 row_ror:1 row_mask:0xf bank_mask:0xf
	v_mov_b32_dpp v172, v82 row_ror:1 row_mask:0xf bank_mask:0xf
	v_mov_b32_e32 v96, v82
	v_add_f32_e32 v92, 1.0, v92
	v_rcp_f32_e32 v92, v92
	v_mov_b32_e32 v97, v86
	v_mul_f32_e32 v91, v91, v92
	v_mul_f32_e32 v90, v90, v91
	v_cvt_pk_bf16_f32 v92, v136, v126
	v_cvt_pk_bf16_f32 v93, v122, v90
	v_mov_b64_e32 v[90:91], s[84:85]
	v_mad_i64_i32 v[94:95], s[20:21], v94, s90, v[90:91]
	v_lshl_add_u64 v[122:123], v[94:95], 0, v[140:141]
	global_store_dwordx2 v[122:123], v[92:93], off nt
	v_cndmask_b32_e64 v93, v146, v160, s[0:1]
	v_cndmask_b32_e64 v92, v172, v166, s[0:1]
	v_mov_b32_dpp v126, v78 row_ror:15 row_mask:0xf bank_mask:0xf
	v_mov_b32_dpp v136, v74 row_ror:15 row_mask:0xf bank_mask:0xf
	v_pk_mul_f32 v[92:93], v[190:191], v[92:93]
	v_cndmask_b32_e64 v95, v148, v126, s[36:37]
	v_cndmask_b32_e64 v94, v152, v136, s[36:37]
	v_pk_fma_f32 v[92:93], v[96:97], v[192:193], v[92:93]
	v_mov_b32_dpp v147, v87 row_ror:1 row_mask:0xf bank_mask:0xf
	v_pk_fma_f32 v[92:93], v[194:195], v[94:95], v[92:93]
	v_mov_b32_dpp v173, v83 row_ror:1 row_mask:0xf bank_mask:0xf
	v_pk_add_f32 v[92:93], v[196:197], v[92:93]
	v_mul_f32_e32 v82, 0xbfb8aa3b, v93
	v_exp_f32_e32 v82, v82
	v_mov_b32_dpp v127, v79 row_ror:15 row_mask:0xf bank_mask:0xf
	v_mov_b32_e32 v86, v83
	v_add_f32_e32 v82, 1.0, v82
	v_rcp_f32_e32 v82, v82
	v_mov_b32_dpp v137, v75 row_ror:15 row_mask:0xf bank_mask:0xf
	v_cndmask_b32_e64 v95, v149, v127, s[36:37]
	v_cndmask_b32_e64 v94, v153, v137, s[36:37]
	v_mul_f32_e32 v82, v93, v82
	v_mul_f32_e32 v96, v92, v82
	v_cndmask_b32_e64 v93, v147, v161, s[0:1]
	v_cndmask_b32_e64 v92, v173, v167, s[0:1]
	v_pk_mul_f32 v[92:93], v[106:107], v[92:93]
	v_pk_fma_f32 v[82:83], v[86:87], v[110:111], v[92:93]
	v_pk_fma_f32 v[82:83], v[114:115], v[94:95], v[82:83]
; __device__ __forceinline__ unsigned cvt_pk_bf16(float lo, float hi) { unsigned r; asm volatile("v_cvt_pk_bf16_f32 %0, %1, %2" : "=v"(r) : "v"(lo), "v"(hi)); return r; }
; __device__ __forceinline__ float sigmoidf_(float x) { return __builtin_amdgcn_rcpf(1.0f + __builtin_amdgcn_exp2f(-x * LOG2E)); }
; __device__ __forceinline__ f32x4 ror1v(const f32x4 v) { return (f32x4){dpp_ror1(v[0]), dpp_ror1(v[1]), dpp_ror1(v[2]), dpp_ror1(v[3])}; }
; __device__ __forceinline__ f32x4 rol1v(const f32x4 v) { return (f32x4){dpp_rol1(v[0]), dpp_rol1(v[1]), dpp_rol1(v[2]), dpp_rol1(v[3])}; }
;     __device__ __forceinline__ void operator()(const f32x4 (&acc)[2][2][4][2], const Unit& u, int wr, int wc, int fr, int fq) const {
;     ...
;                 for (int m = 0; m < 4; ++m) {
;                     const f32x4 cg_ = acc[ai][0][m][n], cv_ = acc[ai][1][m][n];
;                     const f32x4 ug0 = m > 0 ? ror1v(acc[ai][0][m - 1][n]) : hpg, uv0 = m > 0 ? ror1v(acc[ai][1][m - 1][n]) : hpv;
;                     const f32x4 dg0 = m < 3 ? rol1v(acc[ai][0][m + 1][n]) : hng, dv0 = m < 3 ? rol1v(acc[ai][1][m + 1][n]) : hnv;
;                     const f32x4 ug1 = ror1v(cg_), uv1 = ror1v(cv_), dg1 = rol1v(cg_), dv1 = rol1v(cv_);
;                     f32x4 ug, uv, dg, dv;
; #pragma unroll
;                     for (int e = 0; e < 4; ++e) { ug[e] = fr == 0 ? ug0[e] : ug1[e]; uv[e] = fr == 0 ? uv0[e] : uv1[e]; dg[e] = fr == 15 ? dg0[e] : dg1[e]; dv[e] = fr == 15 ? dv0[e] : dv1[e]; }
;                     const f32x4 gc = w0g * ug + w1g * cg_ + w2g * dg + bg, vc = w0v * uv + w1v * cv_ + w2v * dv + bv;
;                     f32x4 r;
; #pragma unroll
;                     for (int e = 0; e < 4; ++e) r[e] = gc[e] * sigmoidf_(gc[e]) * vc[e];
;                     u32x2 w; w.x = cvt_pk_bf16(r[0], r[1]); w.y = cvt_pk_bf16(r[2], r[3]);
;                     *(u32x2*)(ACT + (size_t)(u.pm * BM + ai * HALF + wr * 64 + m * 16 + fr) * FF + ch) = w;
;                     asm volatile("" ::: "memory");
	v_mov_b32_dpp v170, v88 row_ror:1 row_mask:0xf bank_mask:0xf
	v_pk_add_f32 v[82:83], v[118:119], v[82:83]
	v_mov_b32_dpp v174, v84 row_ror:1 row_mask:0xf bank_mask:0xf
	v_mul_f32_e32 v86, 0xbfb8aa3b, v83
	v_exp_f32_e32 v86, v86
	v_mov_b32_e32 v92, v84
	v_add_f32_e32 v86, 1.0, v86
	v_rcp_f32_e32 v86, v86
	v_mov_b32_dpp v128, v80 row_ror:15 row_mask:0xf bank_mask:0xf
	v_mov_b32_dpp v144, v76 row_ror:15 row_mask:0xf bank_mask:0xf
	v_mov_b32_e32 v93, v88
	v_mul_f32_e32 v83, v83, v86
	v_mul_f32_e32 v94, v82, v83
	v_cndmask_b32_e64 v83, v170, v164, s[0:1]
	v_cndmask_b32_e64 v82, v174, v168, s[0:1]
	v_pk_mul_f32 v[82:83], v[142:143], v[82:83]
	v_cndmask_b32_e64 v87, v150, v128, s[36:37]
	v_cndmask_b32_e64 v86, v156, v144, s[36:37]
	v_pk_fma_f32 v[82:83], v[92:93], v[154:155], v[82:83]
	v_pk_fma_f32 v[82:83], v[158:159], v[86:87], v[82:83]
	v_pk_add_f32 v[82:83], v[162:163], v[82:83]
	v_mov_b32_dpp v171, v89 row_ror:1 row_mask:0xf bank_mask:0xf
	v_mul_f32_e32 v84, 0xbfb8aa3b, v83
	v_exp_f32_e32 v84, v84
	v_mov_b32_dpp v175, v85 row_ror:1 row_mask:0xf bank_mask:0xf
	v_add_f32_e32 v84, 1.0, v84
	v_rcp_f32_e32 v84, v84
	v_mov_b32_dpp v129, v81 row_ror:15 row_mask:0xf bank_mask:0xf
	v_mov_b32_dpp v145, v77 row_ror:15 row_mask:0xf bank_mask:0xf
	v_mov_b32_e32 v88, v85
	v_mul_f32_e32 v83, v83, v84
	v_mul_f32_e32 v84, v82, v83
	v_cndmask_b32_e64 v83, v171, v165, s[0:1]
	v_cndmask_b32_e64 v82, v175, v169, s[0:1]
	v_pk_mul_f32 v[82:83], v[108:109], v[82:83]
	v_cndmask_b32_e64 v87, v151, v129, s[36:37]
	v_cndmask_b32_e64 v86, v157, v145, s[36:37]
	v_pk_fma_f32 v[82:83], v[88:89], v[112:113], v[82:83]
	v_pk_fma_f32 v[82:83], v[116:117], v[86:87], v[82:83]
	v_pk_add_f32 v[82:83], v[120:121], v[82:83]
	v_mov_b32_dpp v148, v78 row_ror:1 row_mask:0xf bank_mask:0xf
	v_mul_f32_e32 v85, 0xbfb8aa3b, v83
	v_exp_f32_e32 v85, v85
	v_mov_b32_dpp v152, v74 row_ror:1 row_mask:0xf bank_mask:0xf
	v_mov_b32_e32 v86, v74
	v_add_f32_e32 v85, 1.0, v85
	v_rcp_f32_e32 v85, v85
	v_mov_b32_dpp v88, v70 row_ror:15 row_mask:0xf bank_mask:0xf
	v_mov_b32_e32 v87, v78
	v_mul_f32_e32 v83, v83, v85
	v_mul_f32_e32 v83, v82, v83
	v_cvt_pk_bf16_f32 v82, v96, v94
	v_cvt_pk_bf16_f32 v83, v84, v83
	v_add_u32_e32 v84, 0x90, v0
	v_mad_i64_i32 v[84:85], s[20:21], v84, s90, v[90:91]
	v_lshl_add_u64 v[124:125], v[84:85], 0, v[140:141]
	global_store_dwordx2 v[124:125], v[82:83], off nt
	v_cndmask_b32_e64 v83, v148, v146, s[0:1]
	v_cndmask_b32_e64 v82, v152, v172, s[0:1]
	v_mov_b32_dpp v94, v66 row_ror:15 row_mask:0xf bank_mask:0xf
	v_pk_mul_f32 v[82:83], v[190:191], v[82:83]
	v_cndmask_b32_e64 v85, v126, v88, s[36:37]
	v_cndmask_b32_e64 v84, v136, v94, s[36:37]
	v_pk_fma_f32 v[82:83], v[86:87], v[192:193], v[82:83]
	v_pk_fma_f32 v[82:83], v[194:195], v[84:85], v[82:83]
	v_mov_b32_dpp v149, v79 row_ror:1 row_mask:0xf bank_mask:0xf
	v_pk_add_f32 v[82:83], v[196:197], v[82:83]
	v_mov_b32_dpp v153, v75 row_ror:1 row_mask:0xf bank_mask:0xf
	v_mul_f32_e32 v74, 0xbfb8aa3b, v83
	v_exp_f32_e32 v74, v74
	v_mov_b32_e32 v78, v75
	v_add_f32_e32 v74, 1.0, v74
	v_rcp_f32_e32 v74, v74
	v_mov_b32_dpp v89, v71 row_ror:15 row_mask:0xf bank_mask:0xf
	v_mov_b32_dpp v95, v67 row_ror:15 row_mask:0xf bank_mask:0xf
	v_cndmask_b32_e64 v85, v127, v89, s[36:37]
	v_mul_f32_e32 v74, v83, v74
	v_mul_f32_e32 v86, v82, v74
	v_cndmask_b32_e64 v83, v149, v147, s[0:1]
	v_cndmask_b32_e64 v82, v153, v173, s[0:1]
	v_pk_mul_f32 v[82:83], v[106:107], v[82:83]
	v_cndmask_b32_e64 v84, v137, v95, s[36:37]
	v_pk_fma_f32 v[74:75], v[78:79], v[110:111], v[82:83]
	v_pk_fma_f32 v[74:75], v[114:115], v[84:85], v[74:75]
	v_pk_add_f32 v[74:75], v[118:119], v[74:75]
	v_mov_b32_dpp v150, v80 row_ror:1 row_mask:0xf bank_mask:0xf
	v_mul_f32_e32 v78, 0xbfb8aa3b, v75
	v_exp_f32_e32 v78, v78
	v_mov_b32_dpp v156, v76 row_ror:1 row_mask:0xf bank_mask:0xf
	v_add_f32_e32 v78, 1.0, v78
	v_rcp_f32_e32 v78, v78
	v_mov_b32_dpp v92, v72 row_ror:15 row_mask:0xf bank_mask:0xf
	v_mov_b32_dpp v96, v68 row_ror:15 row_mask:0xf bank_mask:0xf
	v_mov_b32_e32 v82, v76
	v_mul_f32_e32 v75, v75, v78
	v_mul_f32_e32 v84, v74, v75
	v_cndmask_b32_e64 v75, v150, v170, s[0:1]
	v_cndmask_b32_e64 v74, v156, v174, s[0:1]
	v_pk_mul_f32 v[74:75], v[142:143], v[74:75]
	v_mov_b32_e32 v83, v80
	v_cndmask_b32_e64 v79, v128, v92, s[36:37]
	v_cndmask_b32_e64 v78, v144, v96, s[36:37]
	v_pk_fma_f32 v[74:75], v[82:83], v[154:155], v[74:75]
	v_pk_fma_f32 v[74:75], v[158:159], v[78:79], v[74:75]
	v_pk_add_f32 v[74:75], v[162:163], v[74:75]
	v_mov_b32_dpp v151, v81 row_ror:1 row_mask:0xf bank_mask:0xf
	v_mul_f32_e32 v76, 0xbfb8aa3b, v75
	v_exp_f32_e32 v76, v76
	v_mov_b32_dpp v157, v77 row_ror:1 row_mask:0xf bank_mask:0xf
	v_add_f32_e32 v76, 1.0, v76
	v_rcp_f32_e32 v76, v76
	v_mov_b32_dpp v93, v73 row_ror:15 row_mask:0xf bank_mask:0xf
	v_mov_b32_dpp v97, v69 row_ror:15 row_mask:0xf bank_mask:0xf
	v_mov_b32_e32 v80, v77
	v_mul_f32_e32 v75, v75, v76
	v_mul_f32_e32 v76, v74, v75
; __device__ __forceinline__ unsigned cvt_pk_bf16(float lo, float hi) { unsigned r; asm volatile("v_cvt_pk_bf16_f32 %0, %1, %2" : "=v"(r) : "v"(lo), "v"(hi)); return r; }
; __device__ __forceinline__ float sigmoidf_(float x) { return __builtin_amdgcn_rcpf(1.0f + __builtin_amdgcn_exp2f(-x * LOG2E)); }
; __device__ __forceinline__ f32x4 ror1v(const f32x4 v) { return (f32x4){dpp_ror1(v[0]), dpp_ror1(v[1]), dpp_ror1(v[2]), dpp_ror1(v[3])}; }
; __device__ __forceinline__ f32x4 rol1v(const f32x4 v) { return (f32x4){dpp_rol1(v[0]), dpp_rol1(v[1]), dpp_rol1(v[2]), dpp_rol1(v[3])}; }
;     __device__ __forceinline__ void operator()(const f32x4 (&acc)[2][2][4][2], const Unit& u, int wr, int wc, int fr, int fq) const {
;     ...
;             const f32x4 w0g = *(const f32x4*)(cw + ch), w1g = *(const f32x4*)(cw + FF2 + ch), w2g = *(const f32x4*)(cw + 2 * FF2 + ch), bg = *(const f32x4*)(cb + ch);
;             const f32x4 w0v = *(const f32x4*)(cw + FF + ch), w1v = *(const f32x4*)(cw + FF2 + FF + ch), w2v = *(const f32x4*)(cw + 2 * FF2 + FF + ch), bv = *(const f32x4*)(cb + FF + ch);
;     ...
;                 for (int m = 0; m < 4; ++m) {
;                     const f32x4 cg_ = acc[ai][0][m][n], cv_ = acc[ai][1][m][n];
;                     const f32x4 ug0 = m > 0 ? ror1v(acc[ai][0][m - 1][n]) : hpg, uv0 = m > 0 ? ror1v(acc[ai][1][m - 1][n]) : hpv;
;                     const f32x4 dg0 = m < 3 ? rol1v(acc[ai][0][m + 1][n]) : hng, dv0 = m < 3 ? rol1v(acc[ai][1][m + 1][n]) : hnv;
;                     const f32x4 ug1 = ror1v(cg_), uv1 = ror1v(cv_), dg1 = rol1v(cg_), dv1 = rol1v(cv_);
;                     f32x4 ug, uv, dg, dv;
; #pragma unroll
;                     for (int e = 0; e < 4; ++e) { ug[e] = fr == 0 ? ug0[e] : ug1[e]; uv[e] = fr == 0 ? uv0[e] : uv1[e]; dg[e] = fr == 15 ? dg0[e] : dg1[e]; dv[e] = fr == 15 ? dv0[e] : dv1[e]; }
;                     const f32x4 gc = w0g * ug + w1g * cg_ + w2g * dg + bg, vc = w0v * uv + w1v * cv_ + w2v * dv + bv;
;                     f32x4 r;
; #pragma unroll
;                     for (int e = 0; e < 4; ++e) r[e] = gc[e] * sigmoidf_(gc[e]) * vc[e];
;                     u32x2 w; w.x = cvt_pk_bf16(r[0], r[1]); w.y = cvt_pk_bf16(r[2], r[3]);
;                     *(u32x2*)(ACT + (size_t)(u.pm * BM + ai * HALF + wr * 64 + m * 16 + fr) * FF + ch) = w;
;                     asm volatile("" ::: "memory");
	v_cndmask_b32_e64 v75, v151, v171, s[0:1]
	v_cndmask_b32_e64 v74, v157, v175, s[0:1]
	v_pk_mul_f32 v[74:75], v[108:109], v[74:75]
	v_cndmask_b32_e64 v79, v129, v93, s[36:37]
	v_cndmask_b32_e64 v78, v145, v97, s[36:37]
	v_pk_fma_f32 v[74:75], v[80:81], v[112:113], v[74:75]
	v_pk_fma_f32 v[74:75], v[116:117], v[78:79], v[74:75]
	v_mov_b32_e32 v78, v66
	v_pk_add_f32 v[74:75], v[120:121], v[74:75]
	v_mov_b32_e32 v79, v70
	v_mul_f32_e32 v77, 0xbfb8aa3b, v75
	v_exp_f32_e32 v77, v77
	v_mov_b32_dpp v80, v71 row_ror:1 row_mask:0xf bank_mask:0xf
	v_add_f32_e32 v77, 1.0, v77
	v_rcp_f32_e32 v77, v77
	v_mov_b32_dpp v83, v67 row_ror:1 row_mask:0xf bank_mask:0xf
	v_mov_b32_dpp v81, v72 row_ror:1 row_mask:0xf bank_mask:0xf
	v_mul_f32_e32 v75, v75, v77
	v_mul_f32_e32 v75, v74, v75
	v_cvt_pk_bf16_f32 v74, v86, v84
	v_cvt_pk_bf16_f32 v75, v76, v75
	v_add_u32_e32 v76, 0xa0, v0
	v_mad_i64_i32 v[76:77], s[20:21], v76, s90, v[90:91]
	v_lshl_add_u64 v[126:127], v[76:77], 0, v[140:141]
	global_store_dwordx2 v[126:127], v[74:75], off nt
	v_cndmask_b32_e64 v77, v88, v102, s[36:37]
	v_mov_b32_dpp v74, v70 row_ror:1 row_mask:0xf bank_mask:0xf
	v_mov_b32_dpp v76, v66 row_ror:1 row_mask:0xf bank_mask:0xf
	v_cndmask_b32_e64 v75, v74, v148, s[0:1]
	v_cndmask_b32_e64 v74, v76, v152, s[0:1]
	v_pk_mul_f32 v[74:75], v[190:191], v[74:75]
	v_cndmask_b32_e64 v76, v94, v98, s[36:37]
	v_pk_fma_f32 v[74:75], v[78:79], v[192:193], v[74:75]
	v_mov_b32_e32 v70, v67
	v_pk_fma_f32 v[74:75], v[194:195], v[76:77], v[74:75]
	v_cndmask_b32_e64 v77, v89, v103, s[36:37]
	v_pk_add_f32 v[74:75], v[196:197], v[74:75]
	v_cndmask_b32_e64 v76, v95, v99, s[36:37]
	v_mul_f32_e32 v66, 0xbfb8aa3b, v75
	v_exp_f32_e32 v66, v66
	v_mov_b32_dpp v82, v73 row_ror:1 row_mask:0xf bank_mask:0xf
	v_add_f32_e32 v66, 1.0, v66
	v_rcp_f32_e32 v66, v66
	v_mov_b32_dpp v84, v68 row_ror:1 row_mask:0xf bank_mask:0xf
	v_mov_b32_dpp v85, v69 row_ror:1 row_mask:0xf bank_mask:0xf
	v_add_u32_e32 v0, 0xb0, v0
	v_mul_f32_e32 v66, v75, v66
	v_mul_f32_e32 v78, v74, v66
	v_cndmask_b32_e64 v75, v80, v149, s[0:1]
	v_cndmask_b32_e64 v74, v83, v153, s[0:1]
	v_pk_mul_f32 v[74:75], v[106:107], v[74:75]
	v_mov_b32_e32 v106, 0
	v_pk_fma_f32 v[66:67], v[70:71], v[110:111], v[74:75]
	v_mov_b32_e32 v74, v68
	v_pk_fma_f32 v[66:67], v[114:115], v[76:77], v[66:67]
	v_mov_b32_e32 v75, v72
	v_pk_add_f32 v[66:67], v[118:119], v[66:67]
	v_cndmask_b32_e64 v71, v92, v104, s[36:37]
	v_mul_f32_e32 v70, 0xbfb8aa3b, v67
	v_exp_f32_e32 v70, v70
	v_mov_b32_e32 v72, v69
	s_and_b64 vcc, exec, s[42:43]
	v_mov_b32_e32 v110, 0
	v_add_f32_e32 v70, 1.0, v70
	v_rcp_f32_e32 v70, v70
	v_mov_b32_e32 v111, 0
	v_mul_f32_e32 v67, v67, v70
	v_mul_f32_e32 v76, v66, v67
	v_cndmask_b32_e64 v67, v81, v150, s[0:1]
	v_cndmask_b32_e64 v66, v84, v156, s[0:1]
	v_pk_mul_f32 v[66:67], v[142:143], v[66:67]
	v_cndmask_b32_e64 v70, v96, v100, s[36:37]
	v_pk_fma_f32 v[66:67], v[74:75], v[154:155], v[66:67]
	s_nop 0
	v_pk_fma_f32 v[66:67], v[158:159], v[70:71], v[66:67]
	v_cndmask_b32_e64 v71, v93, v105, s[36:37]
	v_pk_add_f32 v[66:67], v[162:163], v[66:67]
	v_cndmask_b32_e64 v70, v97, v101, s[36:37]
	v_mul_f32_e32 v68, 0xbfb8aa3b, v67
	v_exp_f32_e32 v68, v68
	s_nop 0
	v_add_f32_e32 v68, 1.0, v68
	v_rcp_f32_e32 v68, v68
	s_nop 0
	v_mul_f32_e32 v67, v67, v68
	v_mul_f32_e32 v68, v66, v67
	v_cndmask_b32_e64 v67, v82, v151, s[0:1]
	v_cndmask_b32_e64 v66, v85, v157, s[0:1]
	v_pk_mul_f32 v[66:67], v[108:109], v[66:67]
	s_nop 0
	v_pk_fma_f32 v[66:67], v[72:73], v[112:113], v[66:67]
	v_mov_b32_e32 v112, 0
	v_pk_fma_f32 v[66:67], v[116:117], v[70:71], v[66:67]
	v_mov_b32_e32 v113, 0
	v_pk_add_f32 v[66:67], v[120:121], v[66:67]
	s_nop 0
	v_mul_f32_e32 v69, 0xbfb8aa3b, v67
	v_exp_f32_e32 v69, v69
	s_nop 0
	v_add_f32_e32 v69, 1.0, v69
	v_rcp_f32_e32 v69, v69
	s_nop 0
	v_mul_f32_e32 v67, v67, v69
	v_mul_f32_e32 v67, v66, v67
	v_cvt_pk_bf16_f32 v66, v78, v76
	v_cvt_pk_bf16_f32 v67, v68, v67
	v_mad_i64_i32 v[68:69], s[20:21], v0, s90, v[90:91]
	v_lshl_add_u64 v[114:115], v[68:69], 0, v[140:141]
	global_store_dwordx2 v[114:115], v[66:67], off nt
	v_or_b32_e32 v66, 4, v186
	v_ashrrev_i32_e32 v67, 31, v66
	v_lshlrev_b64 v[82:83], 2, v[66:67]
	v_lshl_add_u64 v[66:67], s[54:55], 0, v[82:83]
	v_lshl_add_u64 v[74:75], s[62:63], 0, v[82:83]
	v_lshl_add_u64 v[84:85], s[64:65], 0, v[82:83]
	global_load_dwordx4 v[70:73], v[188:189], off offset:16
	s_nop 0
	global_load_dwordx4 v[66:69], v[66:67], off
	s_nop 0
	global_load_dwordx4 v[74:77], v[74:75], off
	s_nop 0
	global_load_dwordx4 v[78:81], v[184:185], off offset:16
	global_load_dwordx4 v[98:101], v[84:85], off
	v_lshl_add_u64 v[84:85], s[66:67], 0, v[82:83]
	global_load_dwordx4 v[102:105], v[84:85], off
	v_lshl_add_u64 v[84:85], s[12:13], 0, v[82:83]
	v_lshl_add_u64 v[82:83], s[86:87], 0, v[82:83]
	global_load_dwordx4 v[94:97], v[84:85], off
	global_load_dwordx4 v[90:93], v[82:83], off
	s_cbranch_vccnz .LBB0_982
	ds_read_b128 v[110:113], v221

; __device__ __forceinline__ unsigned cvt_pk_bf16(float lo, float hi) { unsigned r; asm volatile("v_cvt_pk_bf16_f32 %0, %1, %2" : "=v"(r) : "v"(lo), "v"(hi)); return r; }
; __device__ __forceinline__ float sigmoidf_(float x) { return __builtin_amdgcn_rcpf(1.0f + __builtin_amdgcn_exp2f(-x * LOG2E)); }
; __device__ __forceinline__ f32x4 ror1v(const f32x4 v) { return (f32x4){dpp_ror1(v[0]), dpp_ror1(v[1]), dpp_ror1(v[2]), dpp_ror1(v[3])}; }
; __device__ __forceinline__ f32x4 rol1v(const f32x4 v) { return (f32x4){dpp_rol1(v[0]), dpp_rol1(v[1]), dpp_rol1(v[2]), dpp_rol1(v[3])}; }
;     __device__ __forceinline__ void operator()(const f32x4 (&acc)[2][2][4][2], const Unit& u, int wr, int wc, int fr, int fq) const {
;     ...
;                 for (int m = 0; m < 4; ++m) {
;                     const f32x4 cg_ = acc[ai][0][m][n], cv_ = acc[ai][1][m][n];
;                     const f32x4 ug0 = m > 0 ? ror1v(acc[ai][0][m - 1][n]) : hpg, uv0 = m > 0 ? ror1v(acc[ai][1][m - 1][n]) : hpv;
;                     const f32x4 dg0 = m < 3 ? rol1v(acc[ai][0][m + 1][n]) : hng, dv0 = m < 3 ? rol1v(acc[ai][1][m + 1][n]) : hnv;
;                     const f32x4 ug1 = ror1v(cg_), uv1 = ror1v(cv_), dg1 = rol1v(cg_), dv1 = rol1v(cv_);
;                     f32x4 ug, uv, dg, dv;
; #pragma unroll
;                     for (int e = 0; e < 4; ++e) { ug[e] = fr == 0 ? ug0[e] : ug1[e]; uv[e] = fr == 0 ? uv0[e] : uv1[e]; dg[e] = fr == 15 ? dg0[e] : dg1[e]; dv[e] = fr == 15 ? dv0[e] : dv1[e]; }
;                     const f32x4 gc = w0g * ug + w1g * cg_ + w2g * dg + bg, vc = w0v * uv + w1v * cv_ + w2v * dv + bv;
;                     f32x4 r;
; #pragma unroll
;                     for (int e = 0; e < 4; ++e) r[e] = gc[e] * sigmoidf_(gc[e]) * vc[e];
;                     u32x2 w; w.x = cvt_pk_bf16(r[0], r[1]); w.y = cvt_pk_bf16(r[2], r[3]);
;                     *(u32x2*)(ACT + (size_t)(u.pm * BM + ai * HALF + wr * 64 + m * 16 + fr) * FF + ch) = w;
;                     asm volatile("" ::: "memory");
.LBB0_988:
	v_mov_b32_dpp v0, v54 row_ror:15 row_mask:0xf bank_mask:0xf
	v_mov_b32_dpp v143, v50 row_ror:15 row_mask:0xf bank_mask:0xf
	v_mov_b32_dpp v147, v62 row_ror:1 row_mask:0xf bank_mask:0xf
	v_mov_b32_dpp v151, v58 row_ror:1 row_mask:0xf bank_mask:0xf
	v_mov_b32_dpp v116, v62 row_ror:15 row_mask:0xf bank_mask:0xf
	v_mov_b32_dpp v117, v58 row_ror:15 row_mask:0xf bank_mask:0xf
	s_waitcnt lgkmcnt(0)
	v_cndmask_b32_e64 v119, v147, v110, s[0:1]
	v_cndmask_b32_e64 v118, v151, v106, s[0:1]
	v_cndmask_b32_e64 v129, v116, v0, s[36:37]
	v_cndmask_b32_e64 v128, v117, v143, s[36:37]
	s_waitcnt vmcnt(3)
	v_mov_b32_e32 v116, v98
	v_mov_b32_e32 v117, v70
	v_pk_mul_f32 v[120:121], v[116:117], v[118:119]
	v_mov_b32_e32 v136, v58
	v_mov_b32_e32 v137, v62
	s_waitcnt vmcnt(2)
	v_mov_b32_e32 v118, v102
	v_mov_b32_e32 v119, v66
	v_pk_fma_f32 v[136:137], v[136:137], v[118:119], v[120:121]
	s_waitcnt vmcnt(1)
	v_mov_b32_e32 v120, v94
	v_mov_b32_e32 v121, v74
	v_pk_fma_f32 v[136:137], v[120:121], v[128:129], v[136:137]
	s_waitcnt vmcnt(0)
	v_mov_b32_e32 v128, v90
	v_mov_b32_e32 v129, v78
	v_pk_add_f32 v[136:137], v[128:129], v[136:137]
	v_mul_f32_e32 v58, 0xbfb8aa3b, v137
	v_exp_f32_e32 v58, v58
	v_mov_b32_dpp v148, v63 row_ror:1 row_mask:0xf bank_mask:0xf
	v_add_f32_e32 v58, 1.0, v58
	v_rcp_f32_e32 v58, v58
	v_mov_b32_dpp v152, v59 row_ror:1 row_mask:0xf bank_mask:0xf
	v_cndmask_b32_e64 v111, v148, v111, s[0:1]
	v_cndmask_b32_e64 v110, v152, v107, s[0:1]
	v_mov_b32_e32 v70, v99
	v_mov_b32_dpp v140, v55 row_ror:15 row_mask:0xf bank_mask:0xf
	v_mov_b32_dpp v144, v51 row_ror:15 row_mask:0xf bank_mask:0xf
	v_mov_b32_dpp v155, v63 row_ror:15 row_mask:0xf bank_mask:0xf
	v_mov_b32_dpp v158, v59 row_ror:15 row_mask:0xf bank_mask:0xf
	v_mul_f32_e32 v58, v137, v58
	v_pk_mul_f32 v[98:99], v[70:71], v[110:111]
	v_mov_b32_e32 v62, v59
	v_mov_b32_e32 v66, v103
	v_mul_f32_e32 v136, v136, v58
	v_cndmask_b32_e64 v107, v155, v140, s[36:37]
	v_cndmask_b32_e64 v106, v158, v144, s[36:37]
	v_pk_fma_f32 v[58:59], v[62:63], v[66:67], v[98:99]
	v_mov_b32_e32 v74, v95
	v_pk_fma_f32 v[58:59], v[74:75], v[106:107], v[58:59]
	v_mov_b32_e32 v78, v91
	v_pk_add_f32 v[58:59], v[78:79], v[58:59]
	v_mul_f32_e32 v62, 0xbfb8aa3b, v59
	v_exp_f32_e32 v62, v62
	v_mov_b32_dpp v149, v64 row_ror:1 row_mask:0xf bank_mask:0xf
	v_add_f32_e32 v62, 1.0, v62
	v_rcp_f32_e32 v62, v62
	v_mov_b32_dpp v153, v60 row_ror:1 row_mask:0xf bank_mask:0xf
	v_mul_f32_e32 v59, v59, v62
	v_mul_f32_e32 v106, v58, v59
	v_cndmask_b32_e64 v63, v149, v112, s[0:1]
	v_cndmask_b32_e64 v62, v153, v108, s[0:1]
	v_mov_b32_e32 v58, v100
	v_mov_b32_e32 v59, v72
	v_mov_b32_dpp v141, v56 row_ror:15 row_mask:0xf bank_mask:0xf
	v_mov_b32_dpp v145, v52 row_ror:15 row_mask:0xf bank_mask:0xf
	v_mov_b32_dpp v156, v64 row_ror:15 row_mask:0xf bank_mask:0xf
	v_mov_b32_dpp v159, v60 row_ror:15 row_mask:0xf bank_mask:0xf
	v_pk_mul_f32 v[90:91], v[58:59], v[62:63]
	v_mov_b32_e32 v98, v60
	v_mov_b32_e32 v99, v64
	v_mov_b32_e32 v62, v104
	v_mov_b32_e32 v63, v68
	v_cndmask_b32_e64 v95, v156, v141, s[36:37]
	v_cndmask_b32_e64 v94, v159, v145, s[36:37]
	v_pk_fma_f32 v[98:99], v[98:99], v[62:63], v[90:91]
	v_mov_b32_e32 v90, v96
	v_mov_b32_e32 v91, v76
	v_pk_fma_f32 v[98:99], v[90:91], v[94:95], v[98:99]
	v_mov_b32_e32 v94, v92
	v_mov_b32_e32 v95, v80
	v_pk_add_f32 v[98:99], v[94:95], v[98:99]
	v_mul_f32_e32 v60, 0xbfb8aa3b, v99
	v_exp_f32_e32 v60, v60
	v_mov_b32_dpp v150, v65 row_ror:1 row_mask:0xf bank_mask:0xf
	v_add_f32_e32 v60, 1.0, v60
	v_rcp_f32_e32 v60, v60
	v_mov_b32_dpp v154, v61 row_ror:1 row_mask:0xf bank_mask:0xf
	v_mul_f32_e32 v60, v99, v60
	v_mul_f32_e32 v92, v98, v60
	v_cndmask_b32_e64 v99, v150, v113, s[0:1]
	v_cndmask_b32_e64 v98, v154, v109, s[0:1]
	v_mov_b32_e32 v72, v101
	v_mov_b32_dpp v142, v57 row_ror:15 row_mask:0xf bank_mask:0xf
	v_mov_b32_dpp v146, v53 row_ror:15 row_mask:0xf bank_mask:0xf
	v_mov_b32_dpp v157, v65 row_ror:15 row_mask:0xf bank_mask:0xf
	v_mov_b32_dpp v160, v61 row_ror:15 row_mask:0xf bank_mask:0xf
	v_pk_mul_f32 v[98:99], v[72:73], v[98:99]
	v_mov_b32_e32 v64, v61
	v_mov_b32_e32 v68, v105
	v_cndmask_b32_e64 v103, v157, v142, s[36:37]
	v_cndmask_b32_e64 v102, v160, v146, s[36:37]
	v_pk_fma_f32 v[60:61], v[64:65], v[68:69], v[98:99]
	v_mov_b32_e32 v76, v97
	v_pk_fma_f32 v[60:61], v[76:77], v[102:103], v[60:61]
	v_mov_b32_e32 v80, v93
	v_pk_add_f32 v[60:61], v[80:81], v[60:61]
	v_mul_f32_e32 v64, 0xbfb8aa3b, v61
	v_exp_f32_e32 v64, v64
	v_mov_b32_dpp v104, v54 row_ror:1 row_mask:0xf bank_mask:0xf
	v_add_f32_e32 v64, 1.0, v64
	v_rcp_f32_e32 v64, v64
	v_mov_b32_dpp v108, v50 row_ror:1 row_mask:0xf bank_mask:0xf
	v_mov_b32_dpp v96, v46 row_ror:15 row_mask:0xf bank_mask:0xf
	v_mul_f32_e32 v61, v61, v64
	v_mul_f32_e32 v61, v60, v61
	v_cvt_pk_bf16_f32 v60, v136, v106
	v_cvt_pk_bf16_f32 v61, v92, v61
	global_store_dwordx2 v[138:139], v[60:61], off offset:8 nt
	v_cndmask_b32_e64 v61, v104, v147, s[0:1]
	v_cndmask_b32_e64 v60, v108, v151, s[0:1]
	v_mov_b32_dpp v100, v42 row_ror:15 row_mask:0xf bank_mask:0xf
	v_pk_mul_f32 v[60:61], v[116:117], v[60:61]
	v_mov_b32_e32 v92, v50
	v_mov_b32_e32 v93, v54
	v_cndmask_b32_e64 v65, v0, v96, s[36:37]
	v_cndmask_b32_e64 v64, v143, v100, s[36:37]
	v_pk_fma_f32 v[60:61], v[92:93], v[118:119], v[60:61]
	v_pk_fma_f32 v[60:61], v[120:121], v[64:65], v[60:61]
	v_pk_add_f32 v[60:61], v[128:129], v[60:61]
	v_mov_b32_dpp v105, v55 row_ror:1 row_mask:0xf bank_mask:0xf
	v_mul_f32_e32 v0, 0xbfb8aa3b, v61
	v_exp_f32_e32 v0, v0
	v_mov_b32_dpp v109, v51 row_ror:1 row_mask:0xf bank_mask:0xf
	v_add_f32_e32 v0, 1.0, v0
	v_rcp_f32_e32 v0, v0
	v_mov_b32_dpp v97, v47 row_ror:15 row_mask:0xf bank_mask:0xf
; __device__ __forceinline__ unsigned cvt_pk_bf16(float lo, float hi) { unsigned r; asm volatile("v_cvt_pk_bf16_f32 %0, %1, %2" : "=v"(r) : "v"(lo), "v"(hi)); return r; }
; __device__ __forceinline__ float sigmoidf_(float x) { return __builtin_amdgcn_rcpf(1.0f + __builtin_amdgcn_exp2f(-x * LOG2E)); }
; __device__ __forceinline__ f32x4 ror1v(const f32x4 v) { return (f32x4){dpp_ror1(v[0]), dpp_ror1(v[1]), dpp_ror1(v[2]), dpp_ror1(v[3])}; }
; __device__ __forceinline__ f32x4 rol1v(const f32x4 v) { return (f32x4){dpp_rol1(v[0]), dpp_rol1(v[1]), dpp_rol1(v[2]), dpp_rol1(v[3])}; }
;     __device__ __forceinline__ void operator()(const f32x4 (&acc)[2][2][4][2], const Unit& u, int wr, int wc, int fr, int fq) const {
;     ...
;                 for (int m = 0; m < 4; ++m) {
;                     const f32x4 cg_ = acc[ai][0][m][n], cv_ = acc[ai][1][m][n];
;                     const f32x4 ug0 = m > 0 ? ror1v(acc[ai][0][m - 1][n]) : hpg, uv0 = m > 0 ? ror1v(acc[ai][1][m - 1][n]) : hpv;
;                     const f32x4 dg0 = m < 3 ? rol1v(acc[ai][0][m + 1][n]) : hng, dv0 = m < 3 ? rol1v(acc[ai][1][m + 1][n]) : hnv;
;                     const f32x4 ug1 = ror1v(cg_), uv1 = ror1v(cv_), dg1 = rol1v(cg_), dv1 = rol1v(cv_);
;                     f32x4 ug, uv, dg, dv;
; #pragma unroll
;                     for (int e = 0; e < 4; ++e) { ug[e] = fr == 0 ? ug0[e] : ug1[e]; uv[e] = fr == 0 ? uv0[e] : uv1[e]; dg[e] = fr == 15 ? dg0[e] : dg1[e]; dv[e] = fr == 15 ? dv0[e] : dv1[e]; }
;                     const f32x4 gc = w0g * ug + w1g * cg_ + w2g * dg + bg, vc = w0v * uv + w1v * cv_ + w2v * dv + bv;
;                     f32x4 r;
; #pragma unroll
;                     for (int e = 0; e < 4; ++e) r[e] = gc[e] * sigmoidf_(gc[e]) * vc[e];
;                     u32x2 w; w.x = cvt_pk_bf16(r[0], r[1]); w.y = cvt_pk_bf16(r[2], r[3]);
;                     *(u32x2*)(ACT + (size_t)(u.pm * BM + ai * HALF + wr * 64 + m * 16 + fr) * FF + ch) = w;
;                     asm volatile("" ::: "memory");
	v_mov_b32_dpp v101, v43 row_ror:15 row_mask:0xf bank_mask:0xf
	v_mov_b32_e32 v54, v51
	v_mul_f32_e32 v0, v61, v0
	v_mul_f32_e32 v0, v60, v0
	v_cndmask_b32_e64 v61, v105, v148, s[0:1]
	v_cndmask_b32_e64 v60, v109, v152, s[0:1]
	v_pk_mul_f32 v[60:61], v[70:71], v[60:61]
	v_cndmask_b32_e64 v65, v140, v97, s[36:37]
	v_cndmask_b32_e64 v64, v144, v101, s[36:37]
	v_pk_fma_f32 v[50:51], v[54:55], v[66:67], v[60:61]
	v_pk_fma_f32 v[50:51], v[74:75], v[64:65], v[50:51]
	v_pk_add_f32 v[50:51], v[78:79], v[50:51]
	v_mov_b32_dpp v106, v56 row_ror:1 row_mask:0xf bank_mask:0xf
	v_mul_f32_e32 v54, 0xbfb8aa3b, v51
	v_exp_f32_e32 v54, v54
	v_mov_b32_dpp v110, v52 row_ror:1 row_mask:0xf bank_mask:0xf
	v_add_f32_e32 v54, 1.0, v54
	v_rcp_f32_e32 v54, v54
	v_mov_b32_dpp v98, v48 row_ror:15 row_mask:0xf bank_mask:0xf
	v_mov_b32_dpp v102, v44 row_ror:15 row_mask:0xf bank_mask:0xf
	v_mov_b32_e32 v60, v52
	v_mul_f32_e32 v51, v51, v54
	v_mul_f32_e32 v64, v50, v51
	v_cndmask_b32_e64 v51, v106, v149, s[0:1]
	v_cndmask_b32_e64 v50, v110, v153, s[0:1]
	v_pk_mul_f32 v[50:51], v[58:59], v[50:51]
	v_mov_b32_e32 v61, v56
	v_cndmask_b32_e64 v55, v141, v98, s[36:37]
	v_cndmask_b32_e64 v54, v145, v102, s[36:37]
	v_pk_fma_f32 v[50:51], v[60:61], v[62:63], v[50:51]
	v_pk_fma_f32 v[50:51], v[90:91], v[54:55], v[50:51]
	v_pk_add_f32 v[50:51], v[94:95], v[50:51]
	v_mov_b32_dpp v107, v57 row_ror:1 row_mask:0xf bank_mask:0xf
	v_mul_f32_e32 v52, 0xbfb8aa3b, v51
	v_exp_f32_e32 v52, v52
	v_mov_b32_dpp v111, v53 row_ror:1 row_mask:0xf bank_mask:0xf
	v_add_f32_e32 v52, 1.0, v52
	v_rcp_f32_e32 v52, v52
	v_mov_b32_dpp v99, v49 row_ror:15 row_mask:0xf bank_mask:0xf
	v_mov_b32_dpp v103, v45 row_ror:15 row_mask:0xf bank_mask:0xf
	v_mov_b32_e32 v56, v53
	v_mul_f32_e32 v51, v51, v52
	v_mul_f32_e32 v52, v50, v51
	v_cndmask_b32_e64 v51, v107, v150, s[0:1]
	v_cndmask_b32_e64 v50, v111, v154, s[0:1]
	v_pk_mul_f32 v[50:51], v[72:73], v[50:51]
	v_cndmask_b32_e64 v55, v142, v99, s[36:37]
	v_cndmask_b32_e64 v54, v146, v103, s[36:37]
	v_pk_fma_f32 v[50:51], v[56:57], v[68:69], v[50:51]
	v_pk_fma_f32 v[50:51], v[76:77], v[54:55], v[50:51]
	v_pk_add_f32 v[50:51], v[80:81], v[50:51]
	v_mov_b32_dpp v93, v46 row_ror:1 row_mask:0xf bank_mask:0xf
	v_mul_f32_e32 v53, 0xbfb8aa3b, v51
	v_exp_f32_e32 v53, v53
	v_mov_b32_dpp v61, v34 row_ror:15 row_mask:0xf bank_mask:0xf
	v_mov_b32_e32 v54, v42
	v_mov_b32_e32 v55, v46
	v_add_f32_e32 v53, 1.0, v53
	v_rcp_f32_e32 v53, v53
	s_nop 0
	v_mul_f32_e32 v51, v51, v53
	v_mul_f32_e32 v51, v50, v51
	v_cvt_pk_bf16_f32 v50, v0, v64
	v_cvt_pk_bf16_f32 v51, v52, v51
	global_store_dwordx2 v[130:131], v[50:51], off offset:8 nt
	v_cndmask_b32_e64 v51, v93, v104, s[0:1]
	v_mov_b32_dpp v131, v42 row_ror:1 row_mask:0xf bank_mask:0xf
	v_cndmask_b32_e64 v50, v131, v108, s[0:1]
	v_mov_b32_dpp v0, v38 row_ror:15 row_mask:0xf bank_mask:0xf
	v_pk_mul_f32 v[50:51], v[116:117], v[50:51]
	v_cndmask_b32_e64 v53, v96, v0, s[36:37]
	v_cndmask_b32_e64 v52, v100, v61, s[36:37]
	v_pk_fma_f32 v[50:51], v[54:55], v[118:119], v[50:51]
	v_mov_b32_dpp v112, v47 row_ror:1 row_mask:0xf bank_mask:0xf
	v_pk_fma_f32 v[50:51], v[120:121], v[52:53], v[50:51]
	v_mov_b32_dpp v136, v43 row_ror:1 row_mask:0xf bank_mask:0xf
	v_pk_add_f32 v[50:51], v[128:129], v[50:51]
	v_mul_f32_e32 v42, 0xbfb8aa3b, v51
	v_exp_f32_e32 v42, v42
	v_mov_b32_dpp v56, v39 row_ror:15 row_mask:0xf bank_mask:0xf
	v_mov_b32_dpp v64, v35 row_ror:15 row_mask:0xf bank_mask:0xf
	v_mov_b32_e32 v46, v43
	v_add_f32_e32 v42, 1.0, v42
	v_rcp_f32_e32 v42, v42
	v_cndmask_b32_e64 v53, v97, v56, s[36:37]
	v_cndmask_b32_e64 v52, v101, v64, s[36:37]
	v_mul_f32_e32 v42, v51, v42
	v_mul_f32_e32 v54, v50, v42
	v_cndmask_b32_e64 v51, v112, v105, s[0:1]
	v_cndmask_b32_e64 v50, v136, v109, s[0:1]
	v_pk_mul_f32 v[50:51], v[70:71], v[50:51]
	v_pk_fma_f32 v[42:43], v[46:47], v[66:67], v[50:51]
	v_mov_b32_dpp v113, v48 row_ror:1 row_mask:0xf bank_mask:0xf
	v_pk_fma_f32 v[42:43], v[74:75], v[52:53], v[42:43]
	v_mov_b32_dpp v137, v44 row_ror:1 row_mask:0xf bank_mask:0xf
	v_pk_add_f32 v[42:43], v[78:79], v[42:43]
	v_mul_f32_e32 v46, 0xbfb8aa3b, v43
	v_exp_f32_e32 v46, v46
	v_mov_b32_dpp v57, v40 row_ror:15 row_mask:0xf bank_mask:0xf
	v_mov_b32_e32 v50, v44
	v_add_f32_e32 v46, 1.0, v46
	v_rcp_f32_e32 v46, v46
	v_mov_b32_dpp v65, v36 row_ror:15 row_mask:0xf bank_mask:0xf
	v_mov_b32_e32 v51, v48
	v_cndmask_b32_e64 v47, v98, v57, s[36:37]
	v_mul_f32_e32 v43, v43, v46
	v_mul_f32_e32 v52, v42, v43
	v_cndmask_b32_e64 v43, v113, v106, s[0:1]
	v_cndmask_b32_e64 v42, v137, v110, s[0:1]
; #define LAS __attribute__((address_space(3)))
; __device__ __forceinline__ unsigned cvt_pk_bf16(float lo, float hi) { unsigned r; asm volatile("v_cvt_pk_bf16_f32 %0, %1, %2" : "=v"(r) : "v"(lo), "v"(hi)); return r; }
; __device__ __forceinline__ float sigmoidf_(float x) { return __builtin_amdgcn_rcpf(1.0f + __builtin_amdgcn_exp2f(-x * LOG2E)); }
; __device__ __forceinline__ f32x4 ror1v(const f32x4 v) { return (f32x4){dpp_ror1(v[0]), dpp_ror1(v[1]), dpp_ror1(v[2]), dpp_ror1(v[3])}; }
;     __device__ __forceinline__ void operator()(const f32x4 (&acc)[2][2][4][2], const Unit& u, int wr, int wc, int fr, int fq) const {
;     ...
;                 const f32x4 hpg = blk > 0 ? *(const LAS f32x4*)(xl + ((blk - 1) * 2 + 1) * 256 + colw + 4 * n) : z4;
;                 const f32x4 hpv = blk > 0 ? *(const LAS f32x4*)(xl + ((blk - 1) * 2 + 1) * 256 + 128 + colw + 4 * n) : z4;
;                 const f32x4 hng = blk < 3 ? *(const LAS f32x4*)(xl + ((blk + 1) * 2 + 0) * 256 + colw + 4 * n) : z4;
;                 const f32x4 hnv = blk < 3 ? *(const LAS f32x4*)(xl + ((blk + 1) * 2 + 0) * 256 + 128 + colw + 4 * n) : z4;
;     ...
;                 for (int m = 0; m < 4; ++m) {
;                     const f32x4 cg_ = acc[ai][0][m][n], cv_ = acc[ai][1][m][n];
;                     const f32x4 ug0 = m > 0 ? ror1v(acc[ai][0][m - 1][n]) : hpg, uv0 = m > 0 ? ror1v(acc[ai][1][m - 1][n]) : hpv;
;                     const f32x4 dg0 = m < 3 ? rol1v(acc[ai][0][m + 1][n]) : hng, dv0 = m < 3 ? rol1v(acc[ai][1][m + 1][n]) : hnv;
;                     const f32x4 ug1 = ror1v(cg_), uv1 = ror1v(cv_), dg1 = rol1v(cg_), dv1 = rol1v(cv_);
;                     f32x4 ug, uv, dg, dv;
; #pragma unroll
;                     for (int e = 0; e < 4; ++e) { ug[e] = fr == 0 ? ug0[e] : ug1[e]; uv[e] = fr == 0 ? uv0[e] : uv1[e]; dg[e] = fr == 15 ? dg0[e] : dg1[e]; dv[e] = fr == 15 ? dv0[e] : dv1[e]; }
;                     const f32x4 gc = w0g * ug + w1g * cg_ + w2g * dg + bg, vc = w0v * uv + w1v * cv_ + w2v * dv + bv;
;                     f32x4 r;
; #pragma unroll
;                     for (int e = 0; e < 4; ++e) r[e] = gc[e] * sigmoidf_(gc[e]) * vc[e];
;                     u32x2 w; w.x = cvt_pk_bf16(r[0], r[1]); w.y = cvt_pk_bf16(r[2], r[3]);
;                     *(u32x2*)(ACT + (size_t)(u.pm * BM + ai * HALF + wr * 64 + m * 16 + fr) * FF + ch) = w;
;                     asm volatile("" ::: "memory");
	v_pk_mul_f32 v[42:43], v[58:59], v[42:43]
	v_cndmask_b32_e64 v46, v102, v65, s[36:37]
	v_pk_fma_f32 v[42:43], v[50:51], v[62:63], v[42:43]
	v_pk_fma_f32 v[42:43], v[90:91], v[46:47], v[42:43]
	v_pk_add_f32 v[42:43], v[94:95], v[42:43]
	v_mov_b32_dpp v130, v49 row_ror:1 row_mask:0xf bank_mask:0xf
	v_mul_f32_e32 v44, 0xbfb8aa3b, v43
	v_exp_f32_e32 v44, v44
	v_mov_b32_dpp v138, v45 row_ror:1 row_mask:0xf bank_mask:0xf
	v_add_f32_e32 v44, 1.0, v44
	v_rcp_f32_e32 v44, v44
	v_mov_b32_dpp v60, v41 row_ror:15 row_mask:0xf bank_mask:0xf
	v_mov_b32_dpp v92, v37 row_ror:15 row_mask:0xf bank_mask:0xf
	v_mov_b32_e32 v48, v45
	v_mul_f32_e32 v43, v43, v44
	v_mul_f32_e32 v44, v42, v43
	v_cndmask_b32_e64 v43, v130, v107, s[0:1]
	v_cndmask_b32_e64 v42, v138, v111, s[0:1]
	v_pk_mul_f32 v[42:43], v[72:73], v[42:43]
	v_cndmask_b32_e64 v47, v99, v60, s[36:37]
	v_cndmask_b32_e64 v46, v103, v92, s[36:37]
	v_pk_fma_f32 v[42:43], v[48:49], v[68:69], v[42:43]
	v_pk_fma_f32 v[42:43], v[76:77], v[46:47], v[42:43]
	v_mov_b32_e32 v46, v34
	v_pk_add_f32 v[42:43], v[80:81], v[42:43]
	v_mov_b32_e32 v47, v38
	v_mul_f32_e32 v45, 0xbfb8aa3b, v43
	v_exp_f32_e32 v45, v45
	v_mov_b32_dpp v48, v39 row_ror:1 row_mask:0xf bank_mask:0xf
	v_add_f32_e32 v45, 1.0, v45
	v_rcp_f32_e32 v45, v45
	v_mov_b32_dpp v51, v35 row_ror:1 row_mask:0xf bank_mask:0xf
	v_mov_b32_dpp v49, v40 row_ror:1 row_mask:0xf bank_mask:0xf
	v_mul_f32_e32 v43, v43, v45
	v_mul_f32_e32 v43, v42, v43
	v_cvt_pk_bf16_f32 v42, v54, v52
	v_cvt_pk_bf16_f32 v43, v44, v43
	global_store_dwordx2 v[132:133], v[42:43], off offset:8 nt
	v_cndmask_b32_e64 v45, v0, v86, s[36:37]
	v_mov_b32_dpp v42, v38 row_ror:1 row_mask:0xf bank_mask:0xf
	v_mov_b32_dpp v44, v34 row_ror:1 row_mask:0xf bank_mask:0xf
	v_cndmask_b32_e64 v43, v42, v93, s[0:1]
	v_cndmask_b32_e64 v42, v44, v131, s[0:1]
	v_pk_mul_f32 v[42:43], v[116:117], v[42:43]
	v_cndmask_b32_e64 v44, v61, v82, s[36:37]
	v_pk_fma_f32 v[42:43], v[46:47], v[118:119], v[42:43]
	v_mov_b32_e32 v38, v35
	v_pk_fma_f32 v[42:43], v[120:121], v[44:45], v[42:43]
	v_cndmask_b32_e64 v45, v56, v87, s[36:37]
	v_pk_add_f32 v[42:43], v[128:129], v[42:43]
	v_cndmask_b32_e64 v44, v64, v83, s[36:37]
	v_mul_f32_e32 v0, 0xbfb8aa3b, v43
	v_exp_f32_e32 v0, v0
	v_mov_b32_dpp v50, v41 row_ror:1 row_mask:0xf bank_mask:0xf
	v_add_f32_e32 v0, 1.0, v0
	v_rcp_f32_e32 v0, v0
	v_mov_b32_dpp v52, v36 row_ror:1 row_mask:0xf bank_mask:0xf
	v_mov_b32_dpp v53, v37 row_ror:1 row_mask:0xf bank_mask:0xf
	v_mul_f32_e32 v0, v43, v0
	v_mul_f32_e32 v0, v42, v0
	v_cndmask_b32_e64 v43, v48, v112, s[0:1]
	v_cndmask_b32_e64 v42, v51, v136, s[0:1]
	v_pk_mul_f32 v[42:43], v[70:71], v[42:43]
	s_and_b64 vcc, exec, s[46:47]
	v_pk_fma_f32 v[34:35], v[38:39], v[66:67], v[42:43]
	v_mov_b32_e32 v42, v36
	v_pk_fma_f32 v[34:35], v[74:75], v[44:45], v[34:35]
	v_mov_b32_e32 v43, v40
	v_pk_add_f32 v[34:35], v[78:79], v[34:35]
	v_cndmask_b32_e64 v39, v57, v88, s[36:37]
	v_mul_f32_e32 v38, 0xbfb8aa3b, v35
	v_exp_f32_e32 v38, v38
	v_mov_b32_e32 v40, v37
	v_mov_b32_e32 v46, 0
	v_mov_b32_e32 v47, 0
	v_add_f32_e32 v38, 1.0, v38
	v_rcp_f32_e32 v38, v38
	v_mov_b32_e32 v48, 0
	v_mul_f32_e32 v35, v35, v38
	v_mul_f32_e32 v44, v34, v35
	v_cndmask_b32_e64 v35, v49, v113, s[0:1]
	v_cndmask_b32_e64 v34, v52, v137, s[0:1]
	v_pk_mul_f32 v[34:35], v[58:59], v[34:35]
	v_cndmask_b32_e64 v38, v65, v84, s[36:37]
	v_pk_fma_f32 v[34:35], v[42:43], v[62:63], v[34:35]
	v_mov_b32_e32 v42, 0
	v_pk_fma_f32 v[34:35], v[90:91], v[38:39], v[34:35]
	v_cndmask_b32_e64 v39, v60, v89, s[36:37]
	v_pk_add_f32 v[34:35], v[94:95], v[34:35]
	v_cndmask_b32_e64 v38, v92, v85, s[36:37]
	v_mul_f32_e32 v36, 0xbfb8aa3b, v35
	v_exp_f32_e32 v36, v36
	v_mov_b32_e32 v49, 0
	v_add_f32_e32 v36, 1.0, v36
	v_rcp_f32_e32 v36, v36
	s_nop 0
	v_mul_f32_e32 v35, v35, v36
	v_mul_f32_e32 v36, v34, v35
	v_cndmask_b32_e64 v35, v50, v130, s[0:1]
	v_cndmask_b32_e64 v34, v53, v138, s[0:1]
	v_pk_mul_f32 v[34:35], v[72:73], v[34:35]
	s_nop 0
	v_pk_fma_f32 v[34:35], v[40:41], v[68:69], v[34:35]
	s_nop 0
	v_pk_fma_f32 v[34:35], v[76:77], v[38:39], v[34:35]
	s_nop 0
	v_pk_add_f32 v[34:35], v[80:81], v[34:35]
	s_nop 0
	v_mul_f32_e32 v37, 0xbfb8aa3b, v35
	v_exp_f32_e32 v37, v37
	s_nop 0
	v_add_f32_e32 v37, 1.0, v37
	v_rcp_f32_e32 v37, v37
	s_nop 0
	v_mul_f32_e32 v35, v35, v37
	v_mul_f32_e32 v35, v34, v35
	v_cvt_pk_bf16_f32 v34, v0, v44
	v_cvt_pk_bf16_f32 v35, v36, v35
	global_store_dwordx2 v[134:135], v[34:35], off offset:8 nt
	s_cbranch_vccnz .LBB0_990
	ds_read_b128 v[46:49], v218 offset:3088

; __device__ __forceinline__ unsigned cvt_pk_bf16(float lo, float hi) { unsigned r; asm volatile("v_cvt_pk_bf16_f32 %0, %1, %2" : "=v"(r) : "v"(lo), "v"(hi)); return r; }
; __device__ __forceinline__ float sigmoidf_(float x) { return __builtin_amdgcn_rcpf(1.0f + __builtin_amdgcn_exp2f(-x * LOG2E)); }
; __device__ __forceinline__ f32x4 ror1v(const f32x4 v) { return (f32x4){dpp_ror1(v[0]), dpp_ror1(v[1]), dpp_ror1(v[2]), dpp_ror1(v[3])}; }
; __device__ __forceinline__ f32x4 rol1v(const f32x4 v) { return (f32x4){dpp_rol1(v[0]), dpp_rol1(v[1]), dpp_rol1(v[2]), dpp_rol1(v[3])}; }
;     __device__ __forceinline__ void operator()(const f32x4 (&acc)[2][2][4][2], const Unit& u, int wr, int wc, int fr, int fq) const {
;     ...
;                 for (int m = 0; m < 4; ++m) {
;                     const f32x4 cg_ = acc[ai][0][m][n], cv_ = acc[ai][1][m][n];
;                     const f32x4 ug0 = m > 0 ? ror1v(acc[ai][0][m - 1][n]) : hpg, uv0 = m > 0 ? ror1v(acc[ai][1][m - 1][n]) : hpv;
;                     const f32x4 dg0 = m < 3 ? rol1v(acc[ai][0][m + 1][n]) : hng, dv0 = m < 3 ? rol1v(acc[ai][1][m + 1][n]) : hnv;
;                     const f32x4 ug1 = ror1v(cg_), uv1 = ror1v(cv_), dg1 = rol1v(cg_), dv1 = rol1v(cv_);
;                     f32x4 ug, uv, dg, dv;
; #pragma unroll
;                     for (int e = 0; e < 4; ++e) { ug[e] = fr == 0 ? ug0[e] : ug1[e]; uv[e] = fr == 0 ? uv0[e] : uv1[e]; dg[e] = fr == 15 ? dg0[e] : dg1[e]; dv[e] = fr == 15 ? dv0[e] : dv1[e]; }
;                     const f32x4 gc = w0g * ug + w1g * cg_ + w2g * dg + bg, vc = w0v * uv + w1v * cv_ + w2v * dv + bv;
;                     f32x4 r;
; #pragma unroll
;                     for (int e = 0; e < 4; ++e) r[e] = gc[e] * sigmoidf_(gc[e]) * vc[e];
;                     u32x2 w; w.x = cvt_pk_bf16(r[0], r[1]); w.y = cvt_pk_bf16(r[2], r[3]);
;                     *(u32x2*)(ACT + (size_t)(u.pm * BM + ai * HALF + wr * 64 + m * 16 + fr) * FF + ch) = w;
;                     asm volatile("" ::: "memory");
.LBB0_996:
	v_mov_b32_dpp v83, v30 row_ror:1 row_mask:0xf bank_mask:0xf
	v_mov_b32_dpp v87, v26 row_ror:1 row_mask:0xf bank_mask:0xf
	v_mov_b32_dpp v0, v22 row_ror:15 row_mask:0xf bank_mask:0xf
	v_mov_b32_dpp v61, v18 row_ror:15 row_mask:0xf bank_mask:0xf
	v_mov_b32_dpp v52, v30 row_ror:15 row_mask:0xf bank_mask:0xf
	v_mov_b32_dpp v54, v26 row_ror:15 row_mask:0xf bank_mask:0xf
	s_waitcnt lgkmcnt(0)
	v_cndmask_b32_e64 v51, v83, v46, s[0:1]
	v_cndmask_b32_e64 v50, v87, v42, s[0:1]
	v_cndmask_b32_e64 v53, v52, v0, s[36:37]
	v_cndmask_b32_e64 v52, v54, v61, s[36:37]
	v_pk_mul_f32 v[50:51], v[116:117], v[50:51]
	v_mov_b32_e32 v54, v26
	v_mov_b32_e32 v55, v30
	v_pk_fma_f32 v[50:51], v[54:55], v[118:119], v[50:51]
	v_pk_fma_f32 v[50:51], v[120:121], v[52:53], v[50:51]
	v_pk_add_f32 v[50:51], v[128:129], v[50:51]
	v_mov_b32_dpp v84, v31 row_ror:1 row_mask:0xf bank_mask:0xf
	v_mul_f32_e32 v26, 0xbfb8aa3b, v51
	v_exp_f32_e32 v26, v26
	v_mov_b32_dpp v88, v27 row_ror:1 row_mask:0xf bank_mask:0xf
	v_cndmask_b32_e64 v47, v84, v47, s[0:1]
	v_cndmask_b32_e64 v46, v88, v43, s[0:1]
	v_mov_b32_dpp v56, v23 row_ror:15 row_mask:0xf bank_mask:0xf
	v_mov_b32_dpp v64, v19 row_ror:15 row_mask:0xf bank_mask:0xf
	v_mov_b32_dpp v93, v31 row_ror:15 row_mask:0xf bank_mask:0xf
	v_mov_b32_dpp v98, v27 row_ror:15 row_mask:0xf bank_mask:0xf
	v_add_f32_e32 v26, 1.0, v26
	v_pk_mul_f32 v[46:47], v[70:71], v[46:47]
	v_mov_b32_e32 v30, v27
	v_rcp_f32_e32 v54, v26
	v_cndmask_b32_e64 v43, v93, v56, s[36:37]
	v_cndmask_b32_e64 v42, v98, v64, s[36:37]
	v_pk_fma_f32 v[26:27], v[30:31], v[66:67], v[46:47]
	v_pk_fma_f32 v[26:27], v[74:75], v[42:43], v[26:27]
	v_pk_add_f32 v[26:27], v[78:79], v[26:27]
	v_mov_b32_dpp v85, v32 row_ror:1 row_mask:0xf bank_mask:0xf
	v_mul_f32_e32 v30, 0xbfb8aa3b, v27
	v_exp_f32_e32 v30, v30
	v_mov_b32_dpp v89, v28 row_ror:1 row_mask:0xf bank_mask:0xf
	v_mul_f32_e32 v31, v51, v54
	v_add_f32_e32 v30, 1.0, v30
	v_mul_f32_e32 v50, v50, v31
	v_rcp_f32_e32 v51, v30
	v_cndmask_b32_e64 v31, v85, v48, s[0:1]
	v_cndmask_b32_e64 v30, v89, v44, s[0:1]
	v_mov_b32_dpp v57, v24 row_ror:15 row_mask:0xf bank_mask:0xf
	v_mov_b32_dpp v65, v20 row_ror:15 row_mask:0xf bank_mask:0xf
	v_mov_b32_dpp v96, v32 row_ror:15 row_mask:0xf bank_mask:0xf
	v_mov_b32_dpp v52, v28 row_ror:15 row_mask:0xf bank_mask:0xf
	v_pk_mul_f32 v[30:31], v[58:59], v[30:31]
	v_mov_b32_e32 v46, v28
	v_mov_b32_e32 v47, v32
	v_cndmask_b32_e64 v43, v96, v57, s[36:37]
	v_cndmask_b32_e64 v42, v52, v65, s[36:37]
	v_pk_fma_f32 v[30:31], v[46:47], v[62:63], v[30:31]
	v_mov_b32_dpp v86, v33 row_ror:1 row_mask:0xf bank_mask:0xf
	v_mov_b32_dpp v92, v29 row_ror:1 row_mask:0xf bank_mask:0xf
	v_pk_fma_f32 v[30:31], v[90:91], v[42:43], v[30:31]
	v_pk_add_f32 v[30:31], v[94:95], v[30:31]
	v_cndmask_b32_e64 v43, v86, v49, s[0:1]
	v_cndmask_b32_e64 v42, v92, v45, s[0:1]
	v_mov_b32_dpp v60, v25 row_ror:15 row_mask:0xf bank_mask:0xf
	v_mov_b32_dpp v82, v21 row_ror:15 row_mask:0xf bank_mask:0xf
	v_mov_b32_dpp v97, v33 row_ror:15 row_mask:0xf bank_mask:0xf
	v_mov_b32_dpp v53, v29 row_ror:15 row_mask:0xf bank_mask:0xf
	v_mul_f32_e32 v28, 0xbfb8aa3b, v31
	v_pk_mul_f32 v[42:43], v[72:73], v[42:43]
	v_mov_b32_e32 v32, v29
	v_exp_f32_e32 v46, v28
	v_cndmask_b32_e64 v45, v97, v60, s[36:37]
	v_cndmask_b32_e64 v44, v53, v82, s[36:37]
	v_pk_fma_f32 v[28:29], v[32:33], v[68:69], v[42:43]
	v_add_f32_e32 v33, 1.0, v46
	v_pk_fma_f32 v[28:29], v[76:77], v[44:45], v[28:29]
	v_rcp_f32_e32 v33, v33
	v_pk_add_f32 v[28:29], v[80:81], v[28:29]
	v_mul_f32_e32 v27, v27, v51
	v_mul_f32_e32 v32, 0xbfb8aa3b, v29
	v_exp_f32_e32 v32, v32
	v_mul_f32_e32 v26, v26, v27
	v_mul_f32_e32 v27, v31, v33
	v_mul_f32_e32 v27, v30, v27
	v_add_f32_e32 v32, 1.0, v32
	v_rcp_f32_e32 v32, v32
	v_cvt_pk_bf16_f32 v26, v50, v26
	v_mul_f32_e32 v29, v29, v32
	v_mul_f32_e32 v28, v28, v29
	v_cvt_pk_bf16_f32 v27, v27, v28
	v_mov_b32_dpp v48, v22 row_ror:1 row_mask:0xf bank_mask:0xf
	v_mov_b32_dpp v52, v18 row_ror:1 row_mask:0xf bank_mask:0xf
	global_store_dwordx2 v[122:123], v[26:27], off offset:8 nt
	v_cndmask_b32_e64 v27, v48, v83, s[0:1]
	v_cndmask_b32_e64 v26, v52, v87, s[0:1]
	v_mov_b32_dpp v32, v14 row_ror:15 row_mask:0xf bank_mask:0xf
	v_mov_b32_dpp v44, v10 row_ror:15 row_mask:0xf bank_mask:0xf
	v_pk_mul_f32 v[26:27], v[116:117], v[26:27]
	v_mov_b32_e32 v30, v18
	v_mov_b32_e32 v31, v22
	v_mov_b32_dpp v49, v23 row_ror:1 row_mask:0xf bank_mask:0xf
	v_mov_b32_dpp v53, v19 row_ror:1 row_mask:0xf bank_mask:0xf
	v_cndmask_b32_e64 v29, v0, v32, s[36:37]
	v_cndmask_b32_e64 v28, v61, v44, s[36:37]
	v_pk_fma_f32 v[26:27], v[30:31], v[118:119], v[26:27]
	v_pk_fma_f32 v[26:27], v[120:121], v[28:29], v[26:27]
	v_cndmask_b32_e64 v29, v49, v84, s[0:1]
	v_cndmask_b32_e64 v28, v53, v88, s[0:1]
	v_mov_b32_dpp v33, v15 row_ror:15 row_mask:0xf bank_mask:0xf
	v_mov_b32_dpp v45, v11 row_ror:15 row_mask:0xf bank_mask:0xf
	v_pk_add_f32 v[26:27], v[128:129], v[26:27]
	v_pk_mul_f32 v[28:29], v[70:71], v[28:29]
	v_mov_b32_e32 v22, v19
	v_mul_f32_e32 v0, 0xbfb8aa3b, v27
	v_cndmask_b32_e64 v31, v56, v33, s[36:37]
	v_cndmask_b32_e64 v30, v64, v45, s[36:37]
	v_pk_fma_f32 v[18:19], v[22:23], v[66:67], v[28:29]
	v_exp_f32_e32 v0, v0
	v_pk_fma_f32 v[18:19], v[74:75], v[30:31], v[18:19]
	v_pk_add_f32 v[18:19], v[78:79], v[18:19]
	v_add_f32_e32 v0, 1.0, v0
	v_mul_f32_e32 v22, 0xbfb8aa3b, v19
	v_exp_f32_e32 v22, v22
	v_rcp_f32_e32 v0, v0
	v_mov_b32_dpp v50, v24 row_ror:1 row_mask:0xf bank_mask:0xf
	v_add_f32_e32 v22, 1.0, v22
	v_mov_b32_dpp v54, v20 row_ror:1 row_mask:0xf bank_mask:0xf
	v_rcp_f32_e32 v30, v22
	v_cndmask_b32_e64 v23, v50, v85, s[0:1]
	v_cndmask_b32_e64 v22, v54, v89, s[0:1]
; __device__ __forceinline__ unsigned cvt_pk_bf16(float lo, float hi) { unsigned r; asm volatile("v_cvt_pk_bf16_f32 %0, %1, %2" : "=v"(r) : "v"(lo), "v"(hi)); return r; }
; __device__ __forceinline__ float sigmoidf_(float x) { return __builtin_amdgcn_rcpf(1.0f + __builtin_amdgcn_exp2f(-x * LOG2E)); }
; __device__ __forceinline__ f32x4 ror1v(const f32x4 v) { return (f32x4){dpp_ror1(v[0]), dpp_ror1(v[1]), dpp_ror1(v[2]), dpp_ror1(v[3])}; }
; __device__ __forceinline__ f32x4 rol1v(const f32x4 v) { return (f32x4){dpp_rol1(v[0]), dpp_rol1(v[1]), dpp_rol1(v[2]), dpp_rol1(v[3])}; }
;     __device__ __forceinline__ void operator()(const f32x4 (&acc)[2][2][4][2], const Unit& u, int wr, int wc, int fr, int fq) const {
;     ...
;                 for (int m = 0; m < 4; ++m) {
;                     const f32x4 cg_ = acc[ai][0][m][n], cv_ = acc[ai][1][m][n];
;                     const f32x4 ug0 = m > 0 ? ror1v(acc[ai][0][m - 1][n]) : hpg, uv0 = m > 0 ? ror1v(acc[ai][1][m - 1][n]) : hpv;
;                     const f32x4 dg0 = m < 3 ? rol1v(acc[ai][0][m + 1][n]) : hng, dv0 = m < 3 ? rol1v(acc[ai][1][m + 1][n]) : hnv;
;                     const f32x4 ug1 = ror1v(cg_), uv1 = ror1v(cv_), dg1 = rol1v(cg_), dv1 = rol1v(cv_);
;                     f32x4 ug, uv, dg, dv;
; #pragma unroll
;                     for (int e = 0; e < 4; ++e) { ug[e] = fr == 0 ? ug0[e] : ug1[e]; uv[e] = fr == 0 ? uv0[e] : uv1[e]; dg[e] = fr == 15 ? dg0[e] : dg1[e]; dv[e] = fr == 15 ? dv0[e] : dv1[e]; }
;                     const f32x4 gc = w0g * ug + w1g * cg_ + w2g * dg + bg, vc = w0v * uv + w1v * cv_ + w2v * dv + bv;
;                     f32x4 r;
; #pragma unroll
;                     for (int e = 0; e < 4; ++e) r[e] = gc[e] * sigmoidf_(gc[e]) * vc[e];
;                     u32x2 w; w.x = cvt_pk_bf16(r[0], r[1]); w.y = cvt_pk_bf16(r[2], r[3]);
;                     *(u32x2*)(ACT + (size_t)(u.pm * BM + ai * HALF + wr * 64 + m * 16 + fr) * FF + ch) = w;
;                     asm volatile("" ::: "memory");
	v_mov_b32_dpp v42, v16 row_ror:15 row_mask:0xf bank_mask:0xf
	v_mov_b32_dpp v46, v12 row_ror:15 row_mask:0xf bank_mask:0xf
	v_mul_f32_e32 v0, v27, v0
	v_pk_mul_f32 v[22:23], v[58:59], v[22:23]
	v_mov_b32_e32 v28, v20
	v_mov_b32_e32 v29, v24
	v_mul_f32_e32 v0, v26, v0
	v_cndmask_b32_e64 v27, v57, v42, s[36:37]
	v_cndmask_b32_e64 v26, v65, v46, s[36:37]
	v_pk_fma_f32 v[22:23], v[28:29], v[62:63], v[22:23]
	v_mov_b32_dpp v51, v25 row_ror:1 row_mask:0xf bank_mask:0xf
	v_mov_b32_dpp v55, v21 row_ror:1 row_mask:0xf bank_mask:0xf
	v_pk_fma_f32 v[22:23], v[90:91], v[26:27], v[22:23]
	v_pk_add_f32 v[22:23], v[94:95], v[22:23]
	v_cndmask_b32_e64 v27, v51, v86, s[0:1]
	v_cndmask_b32_e64 v26, v55, v92, s[0:1]
	v_mov_b32_dpp v43, v17 row_ror:15 row_mask:0xf bank_mask:0xf
	v_mov_b32_dpp v47, v13 row_ror:15 row_mask:0xf bank_mask:0xf
	v_mul_f32_e32 v20, 0xbfb8aa3b, v23
	v_pk_mul_f32 v[26:27], v[72:73], v[26:27]
	v_mov_b32_e32 v24, v21
	v_exp_f32_e32 v31, v20
	v_cndmask_b32_e64 v29, v60, v43, s[36:37]
	v_cndmask_b32_e64 v28, v82, v47, s[36:37]
	v_pk_fma_f32 v[20:21], v[24:25], v[68:69], v[26:27]
	v_add_f32_e32 v25, 1.0, v31
	v_pk_fma_f32 v[20:21], v[76:77], v[28:29], v[20:21]
	v_rcp_f32_e32 v25, v25
	v_pk_add_f32 v[20:21], v[80:81], v[20:21]
	v_mul_f32_e32 v19, v19, v30
	v_mul_f32_e32 v24, 0xbfb8aa3b, v21
	v_exp_f32_e32 v24, v24
	v_mul_f32_e32 v18, v18, v19
	v_mul_f32_e32 v19, v23, v25
	v_mul_f32_e32 v19, v22, v19
	v_add_f32_e32 v24, 1.0, v24
	v_rcp_f32_e32 v24, v24
	s_nop 0
	v_mul_f32_e32 v21, v21, v24
	v_mul_f32_e32 v20, v20, v21
	v_cvt_pk_bf16_f32 v18, v0, v18
	v_cvt_pk_bf16_f32 v19, v19, v20
	v_mov_b32_dpp v31, v14 row_ror:1 row_mask:0xf bank_mask:0xf
	v_mov_b32_dpp v61, v10 row_ror:1 row_mask:0xf bank_mask:0xf
	global_store_dwordx2 v[124:125], v[18:19], off offset:8 nt
	v_cndmask_b32_e64 v19, v31, v48, s[0:1]
	v_cndmask_b32_e64 v18, v61, v52, s[0:1]
	v_mov_b32_dpp v0, v6 row_ror:15 row_mask:0xf bank_mask:0xf
	v_mov_b32_dpp v27, v2 row_ror:15 row_mask:0xf bank_mask:0xf
	v_pk_mul_f32 v[18:19], v[116:117], v[18:19]
	v_mov_b32_e32 v22, v10
	v_mov_b32_e32 v23, v14
	v_cndmask_b32_e64 v21, v32, v0, s[36:37]
	v_cndmask_b32_e64 v20, v44, v27, s[36:37]
	v_pk_fma_f32 v[18:19], v[22:23], v[118:119], v[18:19]
	v_pk_fma_f32 v[18:19], v[120:121], v[20:21], v[18:19]
	v_pk_add_f32 v[18:19], v[128:129], v[18:19]
	v_mov_b32_dpp v56, v15 row_ror:1 row_mask:0xf bank_mask:0xf
	v_mul_f32_e32 v10, 0xbfb8aa3b, v19
	v_exp_f32_e32 v10, v10
	v_mov_b32_dpp v64, v11 row_ror:1 row_mask:0xf bank_mask:0xf
	v_cndmask_b32_e64 v21, v56, v49, s[0:1]
	v_cndmask_b32_e64 v20, v64, v53, s[0:1]
	v_mov_b32_dpp v24, v7 row_ror:15 row_mask:0xf bank_mask:0xf
	v_mov_b32_dpp v28, v3 row_ror:15 row_mask:0xf bank_mask:0xf
	v_add_f32_e32 v10, 1.0, v10
	v_pk_mul_f32 v[20:21], v[70:71], v[20:21]
	v_mov_b32_e32 v14, v11
	v_rcp_f32_e32 v48, v10
	v_cndmask_b32_e64 v23, v33, v24, s[36:37]
	v_cndmask_b32_e64 v22, v45, v28, s[36:37]
	v_pk_fma_f32 v[10:11], v[14:15], v[66:67], v[20:21]
	v_pk_fma_f32 v[10:11], v[74:75], v[22:23], v[10:11]
	v_pk_add_f32 v[10:11], v[78:79], v[10:11]
	v_mov_b32_dpp v57, v16 row_ror:1 row_mask:0xf bank_mask:0xf
	v_mul_f32_e32 v14, 0xbfb8aa3b, v11
	v_exp_f32_e32 v14, v14
	v_mov_b32_dpp v32, v12 row_ror:1 row_mask:0xf bank_mask:0xf
	v_mul_f32_e32 v15, v19, v48
	v_add_f32_e32 v14, 1.0, v14
	v_mul_f32_e32 v22, v18, v15
	v_rcp_f32_e32 v23, v14
	v_cndmask_b32_e64 v15, v57, v50, s[0:1]
	v_cndmask_b32_e64 v14, v32, v54, s[0:1]
	v_mov_b32_dpp v25, v8 row_ror:15 row_mask:0xf bank_mask:0xf
	v_mov_b32_dpp v29, v4 row_ror:15 row_mask:0xf bank_mask:0xf
	v_pk_mul_f32 v[14:15], v[58:59], v[14:15]
	v_mov_b32_e32 v20, v12
	v_mov_b32_e32 v21, v16
	v_cndmask_b32_e64 v19, v42, v25, s[36:37]
	v_cndmask_b32_e64 v18, v46, v29, s[36:37]
	v_pk_fma_f32 v[14:15], v[20:21], v[62:63], v[14:15]
	v_mov_b32_dpp v60, v17 row_ror:1 row_mask:0xf bank_mask:0xf
	v_mov_b32_dpp v44, v13 row_ror:1 row_mask:0xf bank_mask:0xf
	v_pk_fma_f32 v[14:15], v[90:91], v[18:19], v[14:15]
	v_pk_add_f32 v[14:15], v[94:95], v[14:15]
	v_cndmask_b32_e64 v19, v60, v51, s[0:1]
; __device__ __forceinline__ unsigned cvt_pk_bf16(float lo, float hi) { unsigned r; asm volatile("v_cvt_pk_bf16_f32 %0, %1, %2" : "=v"(r) : "v"(lo), "v"(hi)); return r; }
; __device__ __forceinline__ float sigmoidf_(float x) { return __builtin_amdgcn_rcpf(1.0f + __builtin_amdgcn_exp2f(-x * LOG2E)); }
; template <class Epi, class Sched, bool ALIGN_EPI, bool SP2>
; __device__ __forceinline__ void gemm_phase(LAS unsigned char* lds, const int K, const Sched& S, const Epi& E) {
;     ...
;         PG8_WAIT_V(0);
;         if (!has_next) break;
;         if (!Epi::keep(cur)) {
; #pragma unroll
;         for (int a = 0; a < 2; ++a)
; #pragma unroll
;             for (int b = 0; b < 2; ++b)
; #pragma unroll
;                 for (int m = 0; m < 4; ++m)
; #pragma unroll
;                     for (int n = 0; n < 2; ++n) acc[a][b][m][n] = (f32x4){0.f, 0.f, 0.f, 0.f};
;         }
;         cur = nxt; cA = nA; cB = nB; ++ui;
;         if constexpr (ALIGN_EPI) { if (wr == 1) PG8_BAR; }
;     __device__ __forceinline__ void operator()(const f32x4 (&acc)[2][2][4][2], const Unit& u, int wr, int wc, int fr, int fq) const {
;     ...
;                 for (int m = 0; m < 4; ++m) {
;                     const f32x4 cg_ = acc[ai][0][m][n], cv_ = acc[ai][1][m][n];
;                     const f32x4 ug0 = m > 0 ? ror1v(acc[ai][0][m - 1][n]) : hpg, uv0 = m > 0 ? ror1v(acc[ai][1][m - 1][n]) : hpv;
;                     const f32x4 dg0 = m < 3 ? rol1v(acc[ai][0][m + 1][n]) : hng, dv0 = m < 3 ? rol1v(acc[ai][1][m + 1][n]) : hnv;
;                     const f32x4 ug1 = ror1v(cg_), uv1 = ror1v(cv_), dg1 = rol1v(cg_), dv1 = rol1v(cv_);
;                     f32x4 ug, uv, dg, dv;
; #pragma unroll
;                     for (int e = 0; e < 4; ++e) { ug[e] = fr == 0 ? ug0[e] : ug1[e]; uv[e] = fr == 0 ? uv0[e] : uv1[e]; dg[e] = fr == 15 ? dg0[e] : dg1[e]; dv[e] = fr == 15 ? dv0[e] : dv1[e]; }
;                     const f32x4 gc = w0g * ug + w1g * cg_ + w2g * dg + bg, vc = w0v * uv + w1v * cv_ + w2v * dv + bv;
;                     f32x4 r;
; #pragma unroll
;                     for (int e = 0; e < 4; ++e) r[e] = gc[e] * sigmoidf_(gc[e]) * vc[e];
;                     u32x2 w; w.x = cvt_pk_bf16(r[0], r[1]); w.y = cvt_pk_bf16(r[2], r[3]);
;                     *(u32x2*)(ACT + (size_t)(u.pm * BM + ai * HALF + wr * 64 + m * 16 + fr) * FF + ch) = w;
;                     asm volatile("" ::: "memory");
	v_cndmask_b32_e64 v18, v44, v55, s[0:1]
	v_mov_b32_dpp v26, v9 row_ror:15 row_mask:0xf bank_mask:0xf
	v_mov_b32_dpp v30, v5 row_ror:15 row_mask:0xf bank_mask:0xf
	v_mul_f32_e32 v12, 0xbfb8aa3b, v15
	v_pk_mul_f32 v[18:19], v[72:73], v[18:19]
	v_mov_b32_e32 v16, v13
	v_exp_f32_e32 v33, v12
	v_cndmask_b32_e64 v21, v43, v26, s[36:37]
	v_cndmask_b32_e64 v20, v47, v30, s[36:37]
	v_pk_fma_f32 v[12:13], v[16:17], v[68:69], v[18:19]
	v_add_f32_e32 v17, 1.0, v33
	v_pk_fma_f32 v[12:13], v[76:77], v[20:21], v[12:13]
	v_rcp_f32_e32 v17, v17
	v_pk_add_f32 v[12:13], v[80:81], v[12:13]
	v_mul_f32_e32 v11, v11, v23
	v_mul_f32_e32 v16, 0xbfb8aa3b, v13
	v_exp_f32_e32 v16, v16
	v_mul_f32_e32 v10, v10, v11
	v_mul_f32_e32 v11, v15, v17
	v_add_f32_e32 v16, 1.0, v16
	v_rcp_f32_e32 v16, v16
	v_mul_f32_e32 v11, v14, v11
	v_cvt_pk_bf16_f32 v10, v22, v10
	v_mul_f32_e32 v13, v13, v16
	v_mul_f32_e32 v12, v12, v13
	v_cvt_pk_bf16_f32 v11, v11, v12
	global_store_dwordx2 v[126:127], v[10:11], off offset:8 nt
	v_mov_b32_dpp v10, v6 row_ror:1 row_mask:0xf bank_mask:0xf
	v_mov_b32_dpp v12, v2 row_ror:1 row_mask:0xf bank_mask:0xf
	v_cndmask_b32_e64 v11, v10, v31, s[0:1]
	v_cndmask_b32_e64 v10, v12, v61, s[0:1]
	v_pk_mul_f32 v[10:11], v[116:117], v[10:11]
	v_mov_b32_e32 v14, v2
	v_mov_b32_e32 v15, v6
	v_mov_b32_dpp v16, v7 row_ror:1 row_mask:0xf bank_mask:0xf
	v_mov_b32_dpp v19, v3 row_ror:1 row_mask:0xf bank_mask:0xf
	v_cndmask_b32_e64 v13, v0, v38, s[36:37]
	v_cndmask_b32_e64 v12, v27, v34, s[36:37]
	v_pk_fma_f32 v[10:11], v[14:15], v[118:119], v[10:11]
	v_mov_b32_e32 v6, v3
	v_pk_fma_f32 v[10:11], v[120:121], v[12:13], v[10:11]
	v_cndmask_b32_e64 v13, v16, v56, s[0:1]
	v_cndmask_b32_e64 v12, v19, v64, s[0:1]
	v_pk_add_f32 v[10:11], v[128:129], v[10:11]
	v_pk_mul_f32 v[12:13], v[70:71], v[12:13]
	v_mul_f32_e32 v0, 0xbfb8aa3b, v11
	v_cndmask_b32_e64 v15, v24, v39, s[36:37]
	v_cndmask_b32_e64 v14, v28, v35, s[36:37]
	v_pk_fma_f32 v[2:3], v[6:7], v[66:67], v[12:13]
	v_exp_f32_e32 v0, v0
	v_pk_fma_f32 v[2:3], v[74:75], v[14:15], v[2:3]
	v_pk_add_f32 v[2:3], v[78:79], v[2:3]
	v_add_f32_e32 v0, 1.0, v0
	v_mul_f32_e32 v6, 0xbfb8aa3b, v3
	v_exp_f32_e32 v6, v6
	v_rcp_f32_e32 v0, v0
	v_mov_b32_dpp v17, v8 row_ror:1 row_mask:0xf bank_mask:0xf
	v_add_f32_e32 v6, 1.0, v6
	v_mov_b32_dpp v20, v4 row_ror:1 row_mask:0xf bank_mask:0xf
	v_rcp_f32_e32 v14, v6
	v_cndmask_b32_e64 v7, v17, v57, s[0:1]
	v_cndmask_b32_e64 v6, v20, v32, s[0:1]
	v_mul_f32_e32 v0, v11, v0
	v_pk_mul_f32 v[6:7], v[58:59], v[6:7]
	v_mov_b32_e32 v12, v4
	v_mov_b32_e32 v13, v8
	v_mul_f32_e32 v0, v10, v0
	v_cndmask_b32_e64 v11, v25, v40, s[36:37]
	v_cndmask_b32_e64 v10, v29, v36, s[36:37]
	v_pk_fma_f32 v[6:7], v[12:13], v[62:63], v[6:7]
	v_mov_b32_dpp v18, v9 row_ror:1 row_mask:0xf bank_mask:0xf
	v_mov_b32_dpp v21, v5 row_ror:1 row_mask:0xf bank_mask:0xf
	v_pk_fma_f32 v[6:7], v[90:91], v[10:11], v[6:7]
	v_cndmask_b32_e64 v11, v18, v60, s[0:1]
	v_pk_add_f32 v[6:7], v[94:95], v[6:7]
	v_cndmask_b32_e64 v10, v21, v44, s[0:1]
	v_mul_f32_e32 v4, 0xbfb8aa3b, v7
	v_pk_mul_f32 v[10:11], v[72:73], v[10:11]
	v_mov_b32_e32 v8, v5
	v_exp_f32_e32 v15, v4
	v_cndmask_b32_e64 v13, v26, v41, s[36:37]
	v_cndmask_b32_e64 v12, v30, v37, s[36:37]
	v_pk_fma_f32 v[4:5], v[8:9], v[68:69], v[10:11]
	v_add_f32_e32 v9, 1.0, v15
	v_pk_fma_f32 v[4:5], v[76:77], v[12:13], v[4:5]
	v_rcp_f32_e32 v9, v9
	v_pk_add_f32 v[4:5], v[80:81], v[4:5]
	v_mul_f32_e32 v3, v3, v14
	v_mul_f32_e32 v8, 0xbfb8aa3b, v5
	v_exp_f32_e32 v8, v8
	v_mul_f32_e32 v2, v2, v3
	v_mul_f32_e32 v3, v7, v9
	v_mul_f32_e32 v3, v6, v3
	v_add_f32_e32 v8, 1.0, v8
	v_rcp_f32_e32 v8, v8
	v_cvt_pk_bf16_f32 v2, v0, v2
	s_andn2_b64 vcc, exec, s[26:27]
	v_mul_f32_e32 v5, v5, v8
	v_mul_f32_e32 v4, v4, v5
	v_cvt_pk_bf16_f32 v3, v3, v4
	global_store_dwordx2 v[114:115], v[2:3], off offset:8 nt
	s_waitcnt vmcnt(0)
	s_mov_b64 s[24:25], -1
	s_cbranch_vccnz .LBB0_942
	v_readlane_b32 s20, v250, 17
	v_readlane_b32 s21, v250, 18
	s_andn2_b64 vcc, exec, s[20:21]
	s_cbranch_vccnz .LBB0_941
	s_barrier
	s_branch .LBB0_941
